# scan compute waves: prompt blocks 1..126 skip the per-block descriptor code (store, barrier, flip LDS buffer, re-enter hand loop)
# speedup vs baseline: 1.0686x; 1.0238x over previous
; #define LAS __attribute__((address_space(3)))
; __device__ __forceinline__ f32x2 fma2(f32x2 a, f32x2 b, f32x2 c) { return __builtin_elementwise_fma(a, b, c); }
; __device__ __forceinline__ float sum8(float x) { x += dppf<0x141>(x); x += dppf<0x4E>(x); x += dppf<0xB1>(x); return x; }
; __device__ __forceinline__ GOps8 g_ld8(const LAS float* B, int t, int kq, int vidx) {
;     GOps8 o; const LAS float* V = B + t * 256 + kq * 16;
; #pragma unroll
;     for (int h = 0; h < 4; ++h) { o.q[h] = *(const LAS f32x4*)(V + 4 * h); o.k[h] = *(const LAS f32x4*)(V + 128 + 4 * h); }
;     o.v = B[4096 + t * 16 + vidx]; o.sc = *(const LAS f32x4*)(B + 4352 + t * 4); return o;
; }
; template <int TB> __device__ __forceinline__ void gdn_block8(f32x2 (&S)[8], const LAS float* B, int kq, int vidx, float* oo) {
;     float okA = 0.f, okB = 0.f;
;     GOps8 c = g_ld8(B, 0, kq, vidx);
; #pragma unroll 1
;     for (int t0 = 0; t0 < TB; t0 += SCAN_UNR) {
;         float P = 1.f, iP = 1.f;
; #pragma unroll
;         for (int tt = 0; tt < SCAN_UNR; ++tt) {
;             const int t = t0 + tt;
;             const GOps8 n = g_ld8(B, (t + 1) & 15, kq, vidx);
;             const f32x2 k[8] = PAIRS8(c.k), q[8] = PAIRS8(c.q);
;             f32x2 pk = S[0] * k[0], pq = S[0] * q[0];
; #pragma unroll
;             for (int e = 1; e < 8; ++e) { pk = fma2(S[e], k[e], pk); pq = fma2(S[e], q[e], pq); }
;             const float dk = sum8(pk.x + pk.y), dq = sum8(pq.x + pq.y);
;             P *= c.sc.x; iP *= c.sc.w;
;             const float coef = c.sc.y * (c.v - P * dk);
;             const float cs = coef * iP; const f32x2 cf2 = {cs, cs};
; #pragma unroll
;             for (int e = 0; e < 8; ++e) S[e] = fma2(k[e], cf2, S[e]);
;             const float o = P * dq + c.sc.z * coef;
;             okA = (kq == t) ? o : okA; okB = (kq + 8 == t) ? o : okB;
;             c = n;
;         }
.LBB0_984:
.Lgdn16_top:
	v_mov_b32_e32 v97, s48
	ds_read_b128 v[64:67], v159 offset:512
	ds_read_b128 v[48:51], v159 offset:0
	ds_read_b128 v[68:71], v159 offset:528
	ds_read_b128 v[52:55], v159 offset:16
	ds_read_b128 v[72:75], v159 offset:544
	ds_read_b128 v[56:59], v159 offset:32
	ds_read_b128 v[76:79], v159 offset:560
	ds_read_b128 v[60:63], v159 offset:48
	ds_read_b128 v[80:83], v97 offset:0
	ds_read_b32 v84, v160 offset:16384
	ds_read_b128 v[194:197], v159 offset:1536
	ds_read_b128 v[178:181], v159 offset:1024
	ds_read_b128 v[198:201], v159 offset:1552
	ds_read_b128 v[182:185], v159 offset:1040
	ds_read_b128 v[202:205], v159 offset:1568
	ds_read_b128 v[186:189], v159 offset:1056
	ds_read_b128 v[206:209], v159 offset:1584
	s_waitcnt lgkmcnt(7)
	v_pk_mul_f32 v[86:87], v[108:109], v[64:65]
	v_pk_mul_f32 v[88:89], v[108:109], v[48:49]
	v_pk_fma_f32 v[86:87], v[110:111], v[66:67], v[86:87]
	v_pk_fma_f32 v[88:89], v[110:111], v[50:51], v[88:89]
	v_pk_fma_f32 v[86:87], v[112:113], v[68:69], v[86:87]
	v_pk_fma_f32 v[88:89], v[112:113], v[52:53], v[88:89]
	v_pk_fma_f32 v[86:87], v[114:115], v[70:71], v[86:87]
	v_pk_fma_f32 v[88:89], v[114:115], v[54:55], v[88:89]
	v_pk_fma_f32 v[86:87], v[116:117], v[72:73], v[86:87]
	v_pk_fma_f32 v[88:89], v[116:117], v[56:57], v[88:89]
	v_pk_fma_f32 v[86:87], v[118:119], v[74:75], v[86:87]
	v_pk_fma_f32 v[88:89], v[118:119], v[58:59], v[88:89]
	v_pk_fma_f32 v[86:87], v[120:121], v[76:77], v[86:87]
	v_pk_fma_f32 v[88:89], v[120:121], v[60:61], v[88:89]
	v_pk_fma_f32 v[86:87], v[122:123], v[78:79], v[86:87]
	v_pk_fma_f32 v[88:89], v[122:123], v[62:63], v[88:89]
	v_add_f32_e32 v86, v86, v87
	v_add_f32_e32 v88, v88, v89
	ds_read_b128 v[190:193], v159 offset:1072
	v_add_f32_dpp v86, v86, v86 row_half_mirror row_mask:0xf bank_mask:0xf bound_ctrl:1
	v_add_f32_dpp v88, v88, v88 row_half_mirror row_mask:0xf bank_mask:0xf bound_ctrl:1
	ds_read_b128 v[210:213], v97 offset:16
	v_add_f32_dpp v86, v86, v86 quad_perm:[2,3,0,1] row_mask:0xf bank_mask:0xf bound_ctrl:1
	v_add_f32_dpp v88, v88, v88 quad_perm:[2,3,0,1] row_mask:0xf bank_mask:0xf bound_ctrl:1
	ds_read_b32 v214, v160 offset:16448
	v_add_f32_dpp v86, v86, v86 quad_perm:[1,0,3,2] row_mask:0xf bank_mask:0xf bound_ctrl:1
	v_add_f32_dpp v88, v88, v88 quad_perm:[1,0,3,2] row_mask:0xf bank_mask:0xf bound_ctrl:1
	v_fma_f32 v94, -v80, v86, v84
	v_mul_f32_e32 v95, v80, v88
	v_mul_f32_e32 v94, v81, v94
	v_cmp_eq_u32_e32 vcc, 0, v156
	v_mul_f32_e32 v92, v94, v83
	v_fma_f32 v96, v82, v94, v95
	v_pk_fma_f32 v[108:109], v[64:65], v[92:93], v[108:109] op_sel_hi:[1,0,1]
	v_pk_fma_f32 v[110:111], v[66:67], v[92:93], v[110:111] op_sel_hi:[1,0,1]
	v_cndmask_b32_e32 v37, v37, v96, vcc
	v_pk_fma_f32 v[112:113], v[68:69], v[92:93], v[112:113] op_sel_hi:[1,0,1]
	v_pk_fma_f32 v[114:115], v[70:71], v[92:93], v[114:115] op_sel_hi:[1,0,1]
	v_pk_fma_f32 v[116:117], v[72:73], v[92:93], v[116:117] op_sel_hi:[1,0,1]
	v_pk_fma_f32 v[118:119], v[74:75], v[92:93], v[118:119] op_sel_hi:[1,0,1]
	v_pk_fma_f32 v[120:121], v[76:77], v[92:93], v[120:121] op_sel_hi:[1,0,1]
	v_pk_fma_f32 v[122:123], v[78:79], v[92:93], v[122:123] op_sel_hi:[1,0,1]
	ds_read_b128 v[64:67], v159 offset:2560
	ds_read_b128 v[48:51], v159 offset:2048
	ds_read_b128 v[68:71], v159 offset:2576
	ds_read_b128 v[52:55], v159 offset:2064
	ds_read_b128 v[72:75], v159 offset:2592
	ds_read_b128 v[56:59], v159 offset:2080
	ds_read_b128 v[76:79], v159 offset:2608
	s_waitcnt lgkmcnt(7)
	v_pk_mul_f32 v[86:87], v[108:109], v[194:195]
	v_pk_mul_f32 v[88:89], v[108:109], v[178:179]
	v_pk_fma_f32 v[86:87], v[110:111], v[196:197], v[86:87]
	v_pk_fma_f32 v[88:89], v[110:111], v[180:181], v[88:89]
	v_pk_fma_f32 v[86:87], v[112:113], v[198:199], v[86:87]
	v_pk_fma_f32 v[88:89], v[112:113], v[182:183], v[88:89]
	v_mul_f32_e32 v90, v80, v210
	v_mul_f32_e32 v91, v83, v213
	v_pk_fma_f32 v[86:87], v[114:115], v[200:201], v[86:87]
	v_pk_fma_f32 v[88:89], v[114:115], v[184:185], v[88:89]
	v_pk_fma_f32 v[86:87], v[116:117], v[202:203], v[86:87]
	v_pk_fma_f32 v[88:89], v[116:117], v[186:187], v[88:89]
	v_pk_fma_f32 v[86:87], v[118:119], v[204:205], v[86:87]
	v_pk_fma_f32 v[88:89], v[118:119], v[188:189], v[88:89]
	v_pk_fma_f32 v[86:87], v[120:121], v[206:207], v[86:87]
	v_pk_fma_f32 v[88:89], v[120:121], v[190:191], v[88:89]
	v_pk_fma_f32 v[86:87], v[122:123], v[208:209], v[86:87]
	v_pk_fma_f32 v[88:89], v[122:123], v[192:193], v[88:89]
	v_add_f32_e32 v86, v86, v87
	v_add_f32_e32 v88, v88, v89
	ds_read_b128 v[60:63], v159 offset:2096
	v_add_f32_dpp v86, v86, v86 row_half_mirror row_mask:0xf bank_mask:0xf bound_ctrl:1
	v_add_f32_dpp v88, v88, v88 row_half_mirror row_mask:0xf bank_mask:0xf bound_ctrl:1
	ds_read_b128 v[80:83], v97 offset:32
	v_add_f32_dpp v86, v86, v86 quad_perm:[2,3,0,1] row_mask:0xf bank_mask:0xf bound_ctrl:1
	v_add_f32_dpp v88, v88, v88 quad_perm:[2,3,0,1] row_mask:0xf bank_mask:0xf bound_ctrl:1
	ds_read_b32 v84, v160 offset:16512
	v_add_f32_dpp v86, v86, v86 quad_perm:[1,0,3,2] row_mask:0xf bank_mask:0xf bound_ctrl:1
	v_add_f32_dpp v88, v88, v88 quad_perm:[1,0,3,2] row_mask:0xf bank_mask:0xf bound_ctrl:1
	v_fma_f32 v94, -v90, v86, v214
	v_mul_f32_e32 v95, v90, v88
	v_mul_f32_e32 v94, v211, v94
	v_cmp_eq_u32_e32 vcc, 1, v156
	v_mul_f32_e32 v92, v94, v91
	v_fma_f32 v96, v212, v94, v95
	v_pk_fma_f32 v[108:109], v[194:195], v[92:93], v[108:109] op_sel_hi:[1,0,1]
	v_pk_fma_f32 v[110:111], v[196:197], v[92:93], v[110:111] op_sel_hi:[1,0,1]
	v_cndmask_b32_e32 v37, v37, v96, vcc
	v_pk_fma_f32 v[112:113], v[198:199], v[92:93], v[112:113] op_sel_hi:[1,0,1]
	v_pk_fma_f32 v[114:115], v[200:201], v[92:93], v[114:115] op_sel_hi:[1,0,1]
	v_pk_fma_f32 v[116:117], v[202:203], v[92:93], v[116:117] op_sel_hi:[1,0,1]
	v_pk_fma_f32 v[118:119], v[204:205], v[92:93], v[118:119] op_sel_hi:[1,0,1]
	v_pk_fma_f32 v[120:121], v[206:207], v[92:93], v[120:121] op_sel_hi:[1,0,1]
	v_pk_fma_f32 v[122:123], v[208:209], v[92:93], v[122:123] op_sel_hi:[1,0,1]
	ds_read_b128 v[194:197], v159 offset:3584
	ds_read_b128 v[178:181], v159 offset:3072
	ds_read_b128 v[198:201], v159 offset:3600
	ds_read_b128 v[182:185], v159 offset:3088
	ds_read_b128 v[202:205], v159 offset:3616
	ds_read_b128 v[186:189], v159 offset:3104
	ds_read_b128 v[206:209], v159 offset:3632
	s_waitcnt lgkmcnt(7)
; __device__ __forceinline__ f32x2 fma2(f32x2 a, f32x2 b, f32x2 c) { return __builtin_elementwise_fma(a, b, c); }
; __device__ __forceinline__ float sum8(float x) { x += dppf<0x141>(x); x += dppf<0x4E>(x); x += dppf<0xB1>(x); return x; }
; template <int TB> __device__ __forceinline__ void gdn_block8(f32x2 (&S)[8], const LAS float* B, int kq, int vidx, float* oo) {
;     ...
;         for (int tt = 0; tt < SCAN_UNR; ++tt) {
;             const int t = t0 + tt;
;             const GOps8 n = g_ld8(B, (t + 1) & 15, kq, vidx);
;             const f32x2 k[8] = PAIRS8(c.k), q[8] = PAIRS8(c.q);
;             f32x2 pk = S[0] * k[0], pq = S[0] * q[0];
; #pragma unroll
;             for (int e = 1; e < 8; ++e) { pk = fma2(S[e], k[e], pk); pq = fma2(S[e], q[e], pq); }
;             const float dk = sum8(pk.x + pk.y), dq = sum8(pq.x + pq.y);
;             P *= c.sc.x; iP *= c.sc.w;
;             const float coef = c.sc.y * (c.v - P * dk);
;             const float cs = coef * iP; const f32x2 cf2 = {cs, cs};
; #pragma unroll
;             for (int e = 0; e < 8; ++e) S[e] = fma2(k[e], cf2, S[e]);
;             const float o = P * dq + c.sc.z * coef;
;             okA = (kq == t) ? o : okA; okB = (kq + 8 == t) ? o : okB;
;             c = n;
;         }
;         const f32x2 p2 = {P, P};
; #pragma unroll
;         for (int e = 0; e < 8; ++e) S[e] = S[e] * p2;
	v_pk_mul_f32 v[86:87], v[108:109], v[64:65]
	v_pk_mul_f32 v[88:89], v[108:109], v[48:49]
	v_pk_fma_f32 v[86:87], v[110:111], v[66:67], v[86:87]
	v_pk_fma_f32 v[88:89], v[110:111], v[50:51], v[88:89]
	v_pk_fma_f32 v[86:87], v[112:113], v[68:69], v[86:87]
	v_pk_fma_f32 v[88:89], v[112:113], v[52:53], v[88:89]
	v_mul_f32_e32 v90, v90, v80
	v_mul_f32_e32 v91, v91, v83
	v_pk_fma_f32 v[86:87], v[114:115], v[70:71], v[86:87]
	v_pk_fma_f32 v[88:89], v[114:115], v[54:55], v[88:89]
	v_pk_fma_f32 v[86:87], v[116:117], v[72:73], v[86:87]
	v_pk_fma_f32 v[88:89], v[116:117], v[56:57], v[88:89]
	v_pk_fma_f32 v[86:87], v[118:119], v[74:75], v[86:87]
	v_pk_fma_f32 v[88:89], v[118:119], v[58:59], v[88:89]
	v_pk_fma_f32 v[86:87], v[120:121], v[76:77], v[86:87]
	v_pk_fma_f32 v[88:89], v[120:121], v[60:61], v[88:89]
	v_pk_fma_f32 v[86:87], v[122:123], v[78:79], v[86:87]
	v_pk_fma_f32 v[88:89], v[122:123], v[62:63], v[88:89]
	v_add_f32_e32 v86, v86, v87
	v_add_f32_e32 v88, v88, v89
	ds_read_b128 v[190:193], v159 offset:3120
	v_add_f32_dpp v86, v86, v86 row_half_mirror row_mask:0xf bank_mask:0xf bound_ctrl:1
	v_add_f32_dpp v88, v88, v88 row_half_mirror row_mask:0xf bank_mask:0xf bound_ctrl:1
	ds_read_b128 v[210:213], v97 offset:48
	v_add_f32_dpp v86, v86, v86 quad_perm:[2,3,0,1] row_mask:0xf bank_mask:0xf bound_ctrl:1
	v_add_f32_dpp v88, v88, v88 quad_perm:[2,3,0,1] row_mask:0xf bank_mask:0xf bound_ctrl:1
	ds_read_b32 v214, v160 offset:16576
	v_add_f32_dpp v86, v86, v86 quad_perm:[1,0,3,2] row_mask:0xf bank_mask:0xf bound_ctrl:1
	v_add_f32_dpp v88, v88, v88 quad_perm:[1,0,3,2] row_mask:0xf bank_mask:0xf bound_ctrl:1
	v_fma_f32 v94, -v90, v86, v84
	v_mul_f32_e32 v95, v90, v88
	v_mul_f32_e32 v94, v81, v94
	v_cmp_eq_u32_e32 vcc, 2, v156
	v_mul_f32_e32 v92, v94, v91
	v_fma_f32 v96, v82, v94, v95
	v_pk_fma_f32 v[108:109], v[64:65], v[92:93], v[108:109] op_sel_hi:[1,0,1]
	v_pk_fma_f32 v[110:111], v[66:67], v[92:93], v[110:111] op_sel_hi:[1,0,1]
	v_cndmask_b32_e32 v37, v37, v96, vcc
	v_pk_fma_f32 v[112:113], v[68:69], v[92:93], v[112:113] op_sel_hi:[1,0,1]
	v_pk_fma_f32 v[114:115], v[70:71], v[92:93], v[114:115] op_sel_hi:[1,0,1]
	v_pk_fma_f32 v[116:117], v[72:73], v[92:93], v[116:117] op_sel_hi:[1,0,1]
	v_pk_fma_f32 v[118:119], v[74:75], v[92:93], v[118:119] op_sel_hi:[1,0,1]
	v_pk_fma_f32 v[120:121], v[76:77], v[92:93], v[120:121] op_sel_hi:[1,0,1]
	v_pk_fma_f32 v[122:123], v[78:79], v[92:93], v[122:123] op_sel_hi:[1,0,1]
	ds_read_b128 v[64:67], v159 offset:4608
	ds_read_b128 v[48:51], v159 offset:4096
	ds_read_b128 v[68:71], v159 offset:4624
	ds_read_b128 v[52:55], v159 offset:4112
	ds_read_b128 v[72:75], v159 offset:4640
	ds_read_b128 v[56:59], v159 offset:4128
	ds_read_b128 v[76:79], v159 offset:4656
	s_waitcnt lgkmcnt(7)
	v_pk_mul_f32 v[86:87], v[108:109], v[194:195]
	v_pk_mul_f32 v[88:89], v[108:109], v[178:179]
	v_pk_fma_f32 v[86:87], v[110:111], v[196:197], v[86:87]
	v_pk_fma_f32 v[88:89], v[110:111], v[180:181], v[88:89]
	v_pk_fma_f32 v[86:87], v[112:113], v[198:199], v[86:87]
	v_pk_fma_f32 v[88:89], v[112:113], v[182:183], v[88:89]
	v_mul_f32_e32 v90, v90, v210
	v_mul_f32_e32 v91, v91, v213
	v_pk_fma_f32 v[86:87], v[114:115], v[200:201], v[86:87]
	v_pk_fma_f32 v[88:89], v[114:115], v[184:185], v[88:89]
	v_pk_fma_f32 v[86:87], v[116:117], v[202:203], v[86:87]
	v_pk_fma_f32 v[88:89], v[116:117], v[186:187], v[88:89]
	v_pk_fma_f32 v[86:87], v[118:119], v[204:205], v[86:87]
	v_pk_fma_f32 v[88:89], v[118:119], v[188:189], v[88:89]
	v_pk_fma_f32 v[86:87], v[120:121], v[206:207], v[86:87]
	v_pk_fma_f32 v[88:89], v[120:121], v[190:191], v[88:89]
	v_pk_fma_f32 v[86:87], v[122:123], v[208:209], v[86:87]
	v_pk_fma_f32 v[88:89], v[122:123], v[192:193], v[88:89]
	v_add_f32_e32 v86, v86, v87
	v_add_f32_e32 v88, v88, v89
	ds_read_b128 v[60:63], v159 offset:4144
	v_add_f32_dpp v86, v86, v86 row_half_mirror row_mask:0xf bank_mask:0xf bound_ctrl:1
	v_add_f32_dpp v88, v88, v88 row_half_mirror row_mask:0xf bank_mask:0xf bound_ctrl:1
	ds_read_b128 v[80:83], v97 offset:64
	v_add_f32_dpp v86, v86, v86 quad_perm:[2,3,0,1] row_mask:0xf bank_mask:0xf bound_ctrl:1
	v_add_f32_dpp v88, v88, v88 quad_perm:[2,3,0,1] row_mask:0xf bank_mask:0xf bound_ctrl:1
	ds_read_b32 v84, v160 offset:16640
	v_add_f32_dpp v86, v86, v86 quad_perm:[1,0,3,2] row_mask:0xf bank_mask:0xf bound_ctrl:1
	v_add_f32_dpp v88, v88, v88 quad_perm:[1,0,3,2] row_mask:0xf bank_mask:0xf bound_ctrl:1
	v_fma_f32 v94, -v90, v86, v214
	v_mul_f32_e32 v95, v90, v88
	v_mul_f32_e32 v94, v211, v94
	v_cmp_eq_u32_e32 vcc, 3, v156
	v_mul_f32_e32 v92, v94, v91
	v_fma_f32 v96, v212, v94, v95
	v_pk_fma_f32 v[108:109], v[194:195], v[92:93], v[108:109] op_sel_hi:[1,0,1]
	v_pk_fma_f32 v[110:111], v[196:197], v[92:93], v[110:111] op_sel_hi:[1,0,1]
	v_cndmask_b32_e32 v37, v37, v96, vcc
	v_pk_fma_f32 v[112:113], v[198:199], v[92:93], v[112:113] op_sel_hi:[1,0,1]
	v_pk_fma_f32 v[114:115], v[200:201], v[92:93], v[114:115] op_sel_hi:[1,0,1]
	v_pk_fma_f32 v[116:117], v[202:203], v[92:93], v[116:117] op_sel_hi:[1,0,1]
	v_pk_fma_f32 v[118:119], v[204:205], v[92:93], v[118:119] op_sel_hi:[1,0,1]
	v_pk_fma_f32 v[120:121], v[206:207], v[92:93], v[120:121] op_sel_hi:[1,0,1]
	v_pk_fma_f32 v[122:123], v[208:209], v[92:93], v[122:123] op_sel_hi:[1,0,1]
	v_pk_mul_f32 v[108:109], v[90:91], v[108:109] op_sel_hi:[0,1]
	v_pk_mul_f32 v[110:111], v[90:91], v[110:111] op_sel_hi:[0,1]
	v_pk_mul_f32 v[112:113], v[90:91], v[112:113] op_sel_hi:[0,1]
	v_pk_mul_f32 v[114:115], v[90:91], v[114:115] op_sel_hi:[0,1]
	v_pk_mul_f32 v[116:117], v[90:91], v[116:117] op_sel_hi:[0,1]
	v_pk_mul_f32 v[118:119], v[90:91], v[118:119] op_sel_hi:[0,1]
	v_pk_mul_f32 v[120:121], v[90:91], v[120:121] op_sel_hi:[0,1]
	v_pk_mul_f32 v[122:123], v[90:91], v[122:123] op_sel_hi:[0,1]
	ds_read_b128 v[194:197], v159 offset:5632
	ds_read_b128 v[178:181], v159 offset:5120
	ds_read_b128 v[198:201], v159 offset:5648
	ds_read_b128 v[182:185], v159 offset:5136
	ds_read_b128 v[202:205], v159 offset:5664
	ds_read_b128 v[186:189], v159 offset:5152
	ds_read_b128 v[206:209], v159 offset:5680
	s_waitcnt lgkmcnt(7)
; __device__ __forceinline__ f32x2 fma2(f32x2 a, f32x2 b, f32x2 c) { return __builtin_elementwise_fma(a, b, c); }
; __device__ __forceinline__ float sum8(float x) { x += dppf<0x141>(x); x += dppf<0x4E>(x); x += dppf<0xB1>(x); return x; }
; template <int TB> __device__ __forceinline__ void gdn_block8(f32x2 (&S)[8], const LAS float* B, int kq, int vidx, float* oo) {
;     ...
;         for (int tt = 0; tt < SCAN_UNR; ++tt) {
;             const int t = t0 + tt;
;             const GOps8 n = g_ld8(B, (t + 1) & 15, kq, vidx);
;             const f32x2 k[8] = PAIRS8(c.k), q[8] = PAIRS8(c.q);
;             f32x2 pk = S[0] * k[0], pq = S[0] * q[0];
; #pragma unroll
;             for (int e = 1; e < 8; ++e) { pk = fma2(S[e], k[e], pk); pq = fma2(S[e], q[e], pq); }
;             const float dk = sum8(pk.x + pk.y), dq = sum8(pq.x + pq.y);
;             P *= c.sc.x; iP *= c.sc.w;
;             const float coef = c.sc.y * (c.v - P * dk);
;             const float cs = coef * iP; const f32x2 cf2 = {cs, cs};
; #pragma unroll
;             for (int e = 0; e < 8; ++e) S[e] = fma2(k[e], cf2, S[e]);
;             const float o = P * dq + c.sc.z * coef;
;             okA = (kq == t) ? o : okA; okB = (kq + 8 == t) ? o : okB;
;             c = n;
;         }
	v_pk_mul_f32 v[86:87], v[108:109], v[64:65]
	v_pk_mul_f32 v[88:89], v[108:109], v[48:49]
	v_pk_fma_f32 v[86:87], v[110:111], v[66:67], v[86:87]
	v_pk_fma_f32 v[88:89], v[110:111], v[50:51], v[88:89]
	v_pk_fma_f32 v[86:87], v[112:113], v[68:69], v[86:87]
	v_pk_fma_f32 v[88:89], v[112:113], v[52:53], v[88:89]
	v_pk_fma_f32 v[86:87], v[114:115], v[70:71], v[86:87]
	v_pk_fma_f32 v[88:89], v[114:115], v[54:55], v[88:89]
	v_pk_fma_f32 v[86:87], v[116:117], v[72:73], v[86:87]
	v_pk_fma_f32 v[88:89], v[116:117], v[56:57], v[88:89]
	v_pk_fma_f32 v[86:87], v[118:119], v[74:75], v[86:87]
	v_pk_fma_f32 v[88:89], v[118:119], v[58:59], v[88:89]
	v_pk_fma_f32 v[86:87], v[120:121], v[76:77], v[86:87]
	v_pk_fma_f32 v[88:89], v[120:121], v[60:61], v[88:89]
	v_pk_fma_f32 v[86:87], v[122:123], v[78:79], v[86:87]
	v_pk_fma_f32 v[88:89], v[122:123], v[62:63], v[88:89]
	v_add_f32_e32 v86, v86, v87
	v_add_f32_e32 v88, v88, v89
	ds_read_b128 v[190:193], v159 offset:5168
	v_add_f32_dpp v86, v86, v86 row_half_mirror row_mask:0xf bank_mask:0xf bound_ctrl:1
	v_add_f32_dpp v88, v88, v88 row_half_mirror row_mask:0xf bank_mask:0xf bound_ctrl:1
	ds_read_b128 v[210:213], v97 offset:80
	v_add_f32_dpp v86, v86, v86 quad_perm:[2,3,0,1] row_mask:0xf bank_mask:0xf bound_ctrl:1
	v_add_f32_dpp v88, v88, v88 quad_perm:[2,3,0,1] row_mask:0xf bank_mask:0xf bound_ctrl:1
	ds_read_b32 v214, v160 offset:16704
	v_add_f32_dpp v86, v86, v86 quad_perm:[1,0,3,2] row_mask:0xf bank_mask:0xf bound_ctrl:1
	v_add_f32_dpp v88, v88, v88 quad_perm:[1,0,3,2] row_mask:0xf bank_mask:0xf bound_ctrl:1
	v_fma_f32 v94, -v80, v86, v84
	v_mul_f32_e32 v95, v80, v88
	v_mul_f32_e32 v94, v81, v94
	v_cmp_eq_u32_e32 vcc, 4, v156
	v_mul_f32_e32 v92, v94, v83
	v_fma_f32 v96, v82, v94, v95
	v_pk_fma_f32 v[108:109], v[64:65], v[92:93], v[108:109] op_sel_hi:[1,0,1]
	v_pk_fma_f32 v[110:111], v[66:67], v[92:93], v[110:111] op_sel_hi:[1,0,1]
	v_cndmask_b32_e32 v37, v37, v96, vcc
	v_pk_fma_f32 v[112:113], v[68:69], v[92:93], v[112:113] op_sel_hi:[1,0,1]
	v_pk_fma_f32 v[114:115], v[70:71], v[92:93], v[114:115] op_sel_hi:[1,0,1]
	v_pk_fma_f32 v[116:117], v[72:73], v[92:93], v[116:117] op_sel_hi:[1,0,1]
	v_pk_fma_f32 v[118:119], v[74:75], v[92:93], v[118:119] op_sel_hi:[1,0,1]
	v_pk_fma_f32 v[120:121], v[76:77], v[92:93], v[120:121] op_sel_hi:[1,0,1]
	v_pk_fma_f32 v[122:123], v[78:79], v[92:93], v[122:123] op_sel_hi:[1,0,1]
	ds_read_b128 v[64:67], v159 offset:6656
	ds_read_b128 v[48:51], v159 offset:6144
	ds_read_b128 v[68:71], v159 offset:6672
	ds_read_b128 v[52:55], v159 offset:6160
	ds_read_b128 v[72:75], v159 offset:6688
	ds_read_b128 v[56:59], v159 offset:6176
	ds_read_b128 v[76:79], v159 offset:6704
	s_waitcnt lgkmcnt(7)
	v_pk_mul_f32 v[86:87], v[108:109], v[194:195]
	v_pk_mul_f32 v[88:89], v[108:109], v[178:179]
	v_pk_fma_f32 v[86:87], v[110:111], v[196:197], v[86:87]
	v_pk_fma_f32 v[88:89], v[110:111], v[180:181], v[88:89]
	v_pk_fma_f32 v[86:87], v[112:113], v[198:199], v[86:87]
	v_pk_fma_f32 v[88:89], v[112:113], v[182:183], v[88:89]
	v_mul_f32_e32 v90, v80, v210
	v_mul_f32_e32 v91, v83, v213
	v_pk_fma_f32 v[86:87], v[114:115], v[200:201], v[86:87]
	v_pk_fma_f32 v[88:89], v[114:115], v[184:185], v[88:89]
	v_pk_fma_f32 v[86:87], v[116:117], v[202:203], v[86:87]
	v_pk_fma_f32 v[88:89], v[116:117], v[186:187], v[88:89]
	v_pk_fma_f32 v[86:87], v[118:119], v[204:205], v[86:87]
	v_pk_fma_f32 v[88:89], v[118:119], v[188:189], v[88:89]
	v_pk_fma_f32 v[86:87], v[120:121], v[206:207], v[86:87]
	v_pk_fma_f32 v[88:89], v[120:121], v[190:191], v[88:89]
	v_pk_fma_f32 v[86:87], v[122:123], v[208:209], v[86:87]
	v_pk_fma_f32 v[88:89], v[122:123], v[192:193], v[88:89]
	v_add_f32_e32 v86, v86, v87
	v_add_f32_e32 v88, v88, v89
	ds_read_b128 v[60:63], v159 offset:6192
	v_add_f32_dpp v86, v86, v86 row_half_mirror row_mask:0xf bank_mask:0xf bound_ctrl:1
	v_add_f32_dpp v88, v88, v88 row_half_mirror row_mask:0xf bank_mask:0xf bound_ctrl:1
	ds_read_b128 v[80:83], v97 offset:96
	v_add_f32_dpp v86, v86, v86 quad_perm:[2,3,0,1] row_mask:0xf bank_mask:0xf bound_ctrl:1
	v_add_f32_dpp v88, v88, v88 quad_perm:[2,3,0,1] row_mask:0xf bank_mask:0xf bound_ctrl:1
	ds_read_b32 v84, v160 offset:16768
	v_add_f32_dpp v86, v86, v86 quad_perm:[1,0,3,2] row_mask:0xf bank_mask:0xf bound_ctrl:1
	v_add_f32_dpp v88, v88, v88 quad_perm:[1,0,3,2] row_mask:0xf bank_mask:0xf bound_ctrl:1
	v_fma_f32 v94, -v90, v86, v214
	v_mul_f32_e32 v95, v90, v88
	v_mul_f32_e32 v94, v211, v94
	v_cmp_eq_u32_e32 vcc, 5, v156
	v_mul_f32_e32 v92, v94, v91
	v_fma_f32 v96, v212, v94, v95
	v_pk_fma_f32 v[108:109], v[194:195], v[92:93], v[108:109] op_sel_hi:[1,0,1]
	v_pk_fma_f32 v[110:111], v[196:197], v[92:93], v[110:111] op_sel_hi:[1,0,1]
	v_cndmask_b32_e32 v37, v37, v96, vcc
	v_pk_fma_f32 v[112:113], v[198:199], v[92:93], v[112:113] op_sel_hi:[1,0,1]
	v_pk_fma_f32 v[114:115], v[200:201], v[92:93], v[114:115] op_sel_hi:[1,0,1]
	v_pk_fma_f32 v[116:117], v[202:203], v[92:93], v[116:117] op_sel_hi:[1,0,1]
	v_pk_fma_f32 v[118:119], v[204:205], v[92:93], v[118:119] op_sel_hi:[1,0,1]
	v_pk_fma_f32 v[120:121], v[206:207], v[92:93], v[120:121] op_sel_hi:[1,0,1]
	v_pk_fma_f32 v[122:123], v[208:209], v[92:93], v[122:123] op_sel_hi:[1,0,1]
	ds_read_b128 v[194:197], v159 offset:7680
	ds_read_b128 v[178:181], v159 offset:7168
	ds_read_b128 v[198:201], v159 offset:7696
	ds_read_b128 v[182:185], v159 offset:7184
	ds_read_b128 v[202:205], v159 offset:7712
	ds_read_b128 v[186:189], v159 offset:7200
	ds_read_b128 v[206:209], v159 offset:7728
	s_waitcnt lgkmcnt(7)
; __device__ __forceinline__ f32x2 fma2(f32x2 a, f32x2 b, f32x2 c) { return __builtin_elementwise_fma(a, b, c); }
; __device__ __forceinline__ float sum8(float x) { x += dppf<0x141>(x); x += dppf<0x4E>(x); x += dppf<0xB1>(x); return x; }
; template <int TB> __device__ __forceinline__ void gdn_block8(f32x2 (&S)[8], const LAS float* B, int kq, int vidx, float* oo) {
;     ...
;         for (int tt = 0; tt < SCAN_UNR; ++tt) {
;             const int t = t0 + tt;
;             const GOps8 n = g_ld8(B, (t + 1) & 15, kq, vidx);
;             const f32x2 k[8] = PAIRS8(c.k), q[8] = PAIRS8(c.q);
;             f32x2 pk = S[0] * k[0], pq = S[0] * q[0];
; #pragma unroll
;             for (int e = 1; e < 8; ++e) { pk = fma2(S[e], k[e], pk); pq = fma2(S[e], q[e], pq); }
;             const float dk = sum8(pk.x + pk.y), dq = sum8(pq.x + pq.y);
;             P *= c.sc.x; iP *= c.sc.w;
;             const float coef = c.sc.y * (c.v - P * dk);
;             const float cs = coef * iP; const f32x2 cf2 = {cs, cs};
; #pragma unroll
;             for (int e = 0; e < 8; ++e) S[e] = fma2(k[e], cf2, S[e]);
;             const float o = P * dq + c.sc.z * coef;
;             okA = (kq == t) ? o : okA; okB = (kq + 8 == t) ? o : okB;
;             c = n;
;         }
;         const f32x2 p2 = {P, P};
; #pragma unroll
;         for (int e = 0; e < 8; ++e) S[e] = S[e] * p2;
	v_pk_mul_f32 v[86:87], v[108:109], v[64:65]
	v_pk_mul_f32 v[88:89], v[108:109], v[48:49]
	v_pk_fma_f32 v[86:87], v[110:111], v[66:67], v[86:87]
	v_pk_fma_f32 v[88:89], v[110:111], v[50:51], v[88:89]
	v_pk_fma_f32 v[86:87], v[112:113], v[68:69], v[86:87]
	v_pk_fma_f32 v[88:89], v[112:113], v[52:53], v[88:89]
	v_mul_f32_e32 v90, v90, v80
	v_mul_f32_e32 v91, v91, v83
	v_pk_fma_f32 v[86:87], v[114:115], v[70:71], v[86:87]
	v_pk_fma_f32 v[88:89], v[114:115], v[54:55], v[88:89]
	v_pk_fma_f32 v[86:87], v[116:117], v[72:73], v[86:87]
	v_pk_fma_f32 v[88:89], v[116:117], v[56:57], v[88:89]
	v_pk_fma_f32 v[86:87], v[118:119], v[74:75], v[86:87]
	v_pk_fma_f32 v[88:89], v[118:119], v[58:59], v[88:89]
	v_pk_fma_f32 v[86:87], v[120:121], v[76:77], v[86:87]
	v_pk_fma_f32 v[88:89], v[120:121], v[60:61], v[88:89]
	v_pk_fma_f32 v[86:87], v[122:123], v[78:79], v[86:87]
	v_pk_fma_f32 v[88:89], v[122:123], v[62:63], v[88:89]
	v_add_f32_e32 v86, v86, v87
	v_add_f32_e32 v88, v88, v89
	ds_read_b128 v[190:193], v159 offset:7216
	v_add_f32_dpp v86, v86, v86 row_half_mirror row_mask:0xf bank_mask:0xf bound_ctrl:1
	v_add_f32_dpp v88, v88, v88 row_half_mirror row_mask:0xf bank_mask:0xf bound_ctrl:1
	ds_read_b128 v[210:213], v97 offset:112
	v_add_f32_dpp v86, v86, v86 quad_perm:[2,3,0,1] row_mask:0xf bank_mask:0xf bound_ctrl:1
	v_add_f32_dpp v88, v88, v88 quad_perm:[2,3,0,1] row_mask:0xf bank_mask:0xf bound_ctrl:1
	ds_read_b32 v214, v160 offset:16832
	v_add_f32_dpp v86, v86, v86 quad_perm:[1,0,3,2] row_mask:0xf bank_mask:0xf bound_ctrl:1
	v_add_f32_dpp v88, v88, v88 quad_perm:[1,0,3,2] row_mask:0xf bank_mask:0xf bound_ctrl:1
	v_fma_f32 v94, -v90, v86, v84
	v_mul_f32_e32 v95, v90, v88
	v_mul_f32_e32 v94, v81, v94
	v_cmp_eq_u32_e32 vcc, 6, v156
	v_mul_f32_e32 v92, v94, v91
	v_fma_f32 v96, v82, v94, v95
	v_pk_fma_f32 v[108:109], v[64:65], v[92:93], v[108:109] op_sel_hi:[1,0,1]
	v_pk_fma_f32 v[110:111], v[66:67], v[92:93], v[110:111] op_sel_hi:[1,0,1]
	v_cndmask_b32_e32 v37, v37, v96, vcc
	v_pk_fma_f32 v[112:113], v[68:69], v[92:93], v[112:113] op_sel_hi:[1,0,1]
	v_pk_fma_f32 v[114:115], v[70:71], v[92:93], v[114:115] op_sel_hi:[1,0,1]
	v_pk_fma_f32 v[116:117], v[72:73], v[92:93], v[116:117] op_sel_hi:[1,0,1]
	v_pk_fma_f32 v[118:119], v[74:75], v[92:93], v[118:119] op_sel_hi:[1,0,1]
	v_pk_fma_f32 v[120:121], v[76:77], v[92:93], v[120:121] op_sel_hi:[1,0,1]
	v_pk_fma_f32 v[122:123], v[78:79], v[92:93], v[122:123] op_sel_hi:[1,0,1]
	ds_read_b128 v[64:67], v159 offset:8704
	ds_read_b128 v[48:51], v159 offset:8192
	ds_read_b128 v[68:71], v159 offset:8720
	ds_read_b128 v[52:55], v159 offset:8208
	ds_read_b128 v[72:75], v159 offset:8736
	ds_read_b128 v[56:59], v159 offset:8224
	ds_read_b128 v[76:79], v159 offset:8752
	s_waitcnt lgkmcnt(7)
	v_pk_mul_f32 v[86:87], v[108:109], v[194:195]
	v_pk_mul_f32 v[88:89], v[108:109], v[178:179]
	v_pk_fma_f32 v[86:87], v[110:111], v[196:197], v[86:87]
	v_pk_fma_f32 v[88:89], v[110:111], v[180:181], v[88:89]
	v_pk_fma_f32 v[86:87], v[112:113], v[198:199], v[86:87]
	v_pk_fma_f32 v[88:89], v[112:113], v[182:183], v[88:89]
	v_mul_f32_e32 v90, v90, v210
	v_mul_f32_e32 v91, v91, v213
	v_pk_fma_f32 v[86:87], v[114:115], v[200:201], v[86:87]
	v_pk_fma_f32 v[88:89], v[114:115], v[184:185], v[88:89]
	v_pk_fma_f32 v[86:87], v[116:117], v[202:203], v[86:87]
	v_pk_fma_f32 v[88:89], v[116:117], v[186:187], v[88:89]
	v_pk_fma_f32 v[86:87], v[118:119], v[204:205], v[86:87]
	v_pk_fma_f32 v[88:89], v[118:119], v[188:189], v[88:89]
	v_pk_fma_f32 v[86:87], v[120:121], v[206:207], v[86:87]
	v_pk_fma_f32 v[88:89], v[120:121], v[190:191], v[88:89]
	v_pk_fma_f32 v[86:87], v[122:123], v[208:209], v[86:87]
	v_pk_fma_f32 v[88:89], v[122:123], v[192:193], v[88:89]
	v_add_f32_e32 v86, v86, v87
	v_add_f32_e32 v88, v88, v89
	ds_read_b128 v[60:63], v159 offset:8240
	v_add_f32_dpp v86, v86, v86 row_half_mirror row_mask:0xf bank_mask:0xf bound_ctrl:1
	v_add_f32_dpp v88, v88, v88 row_half_mirror row_mask:0xf bank_mask:0xf bound_ctrl:1
	ds_read_b128 v[80:83], v97 offset:128
	v_add_f32_dpp v86, v86, v86 quad_perm:[2,3,0,1] row_mask:0xf bank_mask:0xf bound_ctrl:1
	v_add_f32_dpp v88, v88, v88 quad_perm:[2,3,0,1] row_mask:0xf bank_mask:0xf bound_ctrl:1
	ds_read_b32 v84, v160 offset:16896
	v_add_f32_dpp v86, v86, v86 quad_perm:[1,0,3,2] row_mask:0xf bank_mask:0xf bound_ctrl:1
	v_add_f32_dpp v88, v88, v88 quad_perm:[1,0,3,2] row_mask:0xf bank_mask:0xf bound_ctrl:1
	v_fma_f32 v94, -v90, v86, v214
	v_mul_f32_e32 v95, v90, v88
	v_mul_f32_e32 v94, v211, v94
	v_cmp_eq_u32_e32 vcc, 7, v156
	v_mul_f32_e32 v92, v94, v91
	v_fma_f32 v96, v212, v94, v95
	v_pk_fma_f32 v[108:109], v[194:195], v[92:93], v[108:109] op_sel_hi:[1,0,1]
	v_pk_fma_f32 v[110:111], v[196:197], v[92:93], v[110:111] op_sel_hi:[1,0,1]
	v_cndmask_b32_e32 v37, v37, v96, vcc
	v_pk_fma_f32 v[112:113], v[198:199], v[92:93], v[112:113] op_sel_hi:[1,0,1]
	v_pk_fma_f32 v[114:115], v[200:201], v[92:93], v[114:115] op_sel_hi:[1,0,1]
	v_pk_fma_f32 v[116:117], v[202:203], v[92:93], v[116:117] op_sel_hi:[1,0,1]
	v_pk_fma_f32 v[118:119], v[204:205], v[92:93], v[118:119] op_sel_hi:[1,0,1]
	v_pk_fma_f32 v[120:121], v[206:207], v[92:93], v[120:121] op_sel_hi:[1,0,1]
	v_pk_fma_f32 v[122:123], v[208:209], v[92:93], v[122:123] op_sel_hi:[1,0,1]
	v_pk_mul_f32 v[108:109], v[90:91], v[108:109] op_sel_hi:[0,1]
	v_pk_mul_f32 v[110:111], v[90:91], v[110:111] op_sel_hi:[0,1]
	v_pk_mul_f32 v[112:113], v[90:91], v[112:113] op_sel_hi:[0,1]
	v_pk_mul_f32 v[114:115], v[90:91], v[114:115] op_sel_hi:[0,1]
	v_pk_mul_f32 v[116:117], v[90:91], v[116:117] op_sel_hi:[0,1]
	v_pk_mul_f32 v[118:119], v[90:91], v[118:119] op_sel_hi:[0,1]
	v_pk_mul_f32 v[120:121], v[90:91], v[120:121] op_sel_hi:[0,1]
	v_pk_mul_f32 v[122:123], v[90:91], v[122:123] op_sel_hi:[0,1]
	ds_read_b128 v[194:197], v159 offset:9728
	ds_read_b128 v[178:181], v159 offset:9216
	ds_read_b128 v[198:201], v159 offset:9744
	ds_read_b128 v[182:185], v159 offset:9232
	ds_read_b128 v[202:205], v159 offset:9760
	ds_read_b128 v[186:189], v159 offset:9248
	ds_read_b128 v[206:209], v159 offset:9776
	s_waitcnt lgkmcnt(7)
; __device__ __forceinline__ f32x2 fma2(f32x2 a, f32x2 b, f32x2 c) { return __builtin_elementwise_fma(a, b, c); }
; __device__ __forceinline__ float sum8(float x) { x += dppf<0x141>(x); x += dppf<0x4E>(x); x += dppf<0xB1>(x); return x; }
; template <int TB> __device__ __forceinline__ void gdn_block8(f32x2 (&S)[8], const LAS float* B, int kq, int vidx, float* oo) {
;     ...
;         for (int tt = 0; tt < SCAN_UNR; ++tt) {
;             const int t = t0 + tt;
;             const GOps8 n = g_ld8(B, (t + 1) & 15, kq, vidx);
;             const f32x2 k[8] = PAIRS8(c.k), q[8] = PAIRS8(c.q);
;             f32x2 pk = S[0] * k[0], pq = S[0] * q[0];
; #pragma unroll
;             for (int e = 1; e < 8; ++e) { pk = fma2(S[e], k[e], pk); pq = fma2(S[e], q[e], pq); }
;             const float dk = sum8(pk.x + pk.y), dq = sum8(pq.x + pq.y);
;             P *= c.sc.x; iP *= c.sc.w;
;             const float coef = c.sc.y * (c.v - P * dk);
;             const float cs = coef * iP; const f32x2 cf2 = {cs, cs};
; #pragma unroll
;             for (int e = 0; e < 8; ++e) S[e] = fma2(k[e], cf2, S[e]);
;             const float o = P * dq + c.sc.z * coef;
;             okA = (kq == t) ? o : okA; okB = (kq + 8 == t) ? o : okB;
;             c = n;
;         }
	v_pk_mul_f32 v[86:87], v[108:109], v[64:65]
	v_pk_mul_f32 v[88:89], v[108:109], v[48:49]
	v_pk_fma_f32 v[86:87], v[110:111], v[66:67], v[86:87]
	v_pk_fma_f32 v[88:89], v[110:111], v[50:51], v[88:89]
	v_pk_fma_f32 v[86:87], v[112:113], v[68:69], v[86:87]
	v_pk_fma_f32 v[88:89], v[112:113], v[52:53], v[88:89]
	v_pk_fma_f32 v[86:87], v[114:115], v[70:71], v[86:87]
	v_pk_fma_f32 v[88:89], v[114:115], v[54:55], v[88:89]
	v_pk_fma_f32 v[86:87], v[116:117], v[72:73], v[86:87]
	v_pk_fma_f32 v[88:89], v[116:117], v[56:57], v[88:89]
	v_pk_fma_f32 v[86:87], v[118:119], v[74:75], v[86:87]
	v_pk_fma_f32 v[88:89], v[118:119], v[58:59], v[88:89]
	v_pk_fma_f32 v[86:87], v[120:121], v[76:77], v[86:87]
	v_pk_fma_f32 v[88:89], v[120:121], v[60:61], v[88:89]
	v_pk_fma_f32 v[86:87], v[122:123], v[78:79], v[86:87]
	v_pk_fma_f32 v[88:89], v[122:123], v[62:63], v[88:89]
	v_add_f32_e32 v86, v86, v87
	v_add_f32_e32 v88, v88, v89
	ds_read_b128 v[190:193], v159 offset:9264
	v_add_f32_dpp v86, v86, v86 row_half_mirror row_mask:0xf bank_mask:0xf bound_ctrl:1
	v_add_f32_dpp v88, v88, v88 row_half_mirror row_mask:0xf bank_mask:0xf bound_ctrl:1
	ds_read_b128 v[210:213], v97 offset:144
	v_add_f32_dpp v86, v86, v86 quad_perm:[2,3,0,1] row_mask:0xf bank_mask:0xf bound_ctrl:1
	v_add_f32_dpp v88, v88, v88 quad_perm:[2,3,0,1] row_mask:0xf bank_mask:0xf bound_ctrl:1
	ds_read_b32 v214, v160 offset:16960
	v_add_f32_dpp v86, v86, v86 quad_perm:[1,0,3,2] row_mask:0xf bank_mask:0xf bound_ctrl:1
	v_add_f32_dpp v88, v88, v88 quad_perm:[1,0,3,2] row_mask:0xf bank_mask:0xf bound_ctrl:1
	v_fma_f32 v94, -v80, v86, v84
	v_mul_f32_e32 v95, v80, v88
	v_mul_f32_e32 v94, v81, v94
	v_cmp_eq_u32_e32 vcc, 0, v156
	v_mul_f32_e32 v92, v94, v83
	v_fma_f32 v96, v82, v94, v95
	v_pk_fma_f32 v[108:109], v[64:65], v[92:93], v[108:109] op_sel_hi:[1,0,1]
	v_pk_fma_f32 v[110:111], v[66:67], v[92:93], v[110:111] op_sel_hi:[1,0,1]
	v_cndmask_b32_e32 v36, v36, v96, vcc
	v_pk_fma_f32 v[112:113], v[68:69], v[92:93], v[112:113] op_sel_hi:[1,0,1]
	v_pk_fma_f32 v[114:115], v[70:71], v[92:93], v[114:115] op_sel_hi:[1,0,1]
	v_pk_fma_f32 v[116:117], v[72:73], v[92:93], v[116:117] op_sel_hi:[1,0,1]
	v_pk_fma_f32 v[118:119], v[74:75], v[92:93], v[118:119] op_sel_hi:[1,0,1]
	v_pk_fma_f32 v[120:121], v[76:77], v[92:93], v[120:121] op_sel_hi:[1,0,1]
	v_pk_fma_f32 v[122:123], v[78:79], v[92:93], v[122:123] op_sel_hi:[1,0,1]
	ds_read_b128 v[64:67], v159 offset:10752
	ds_read_b128 v[48:51], v159 offset:10240
	ds_read_b128 v[68:71], v159 offset:10768
	ds_read_b128 v[52:55], v159 offset:10256
	ds_read_b128 v[72:75], v159 offset:10784
	ds_read_b128 v[56:59], v159 offset:10272
	ds_read_b128 v[76:79], v159 offset:10800
	s_waitcnt lgkmcnt(7)
	v_pk_mul_f32 v[86:87], v[108:109], v[194:195]
	v_pk_mul_f32 v[88:89], v[108:109], v[178:179]
	v_pk_fma_f32 v[86:87], v[110:111], v[196:197], v[86:87]
	v_pk_fma_f32 v[88:89], v[110:111], v[180:181], v[88:89]
	v_pk_fma_f32 v[86:87], v[112:113], v[198:199], v[86:87]
	v_pk_fma_f32 v[88:89], v[112:113], v[182:183], v[88:89]
	v_mul_f32_e32 v90, v80, v210
	v_mul_f32_e32 v91, v83, v213
	v_pk_fma_f32 v[86:87], v[114:115], v[200:201], v[86:87]
	v_pk_fma_f32 v[88:89], v[114:115], v[184:185], v[88:89]
	v_pk_fma_f32 v[86:87], v[116:117], v[202:203], v[86:87]
	v_pk_fma_f32 v[88:89], v[116:117], v[186:187], v[88:89]
	v_pk_fma_f32 v[86:87], v[118:119], v[204:205], v[86:87]
	v_pk_fma_f32 v[88:89], v[118:119], v[188:189], v[88:89]
	v_pk_fma_f32 v[86:87], v[120:121], v[206:207], v[86:87]
	v_pk_fma_f32 v[88:89], v[120:121], v[190:191], v[88:89]
	v_pk_fma_f32 v[86:87], v[122:123], v[208:209], v[86:87]
	v_pk_fma_f32 v[88:89], v[122:123], v[192:193], v[88:89]
	v_add_f32_e32 v86, v86, v87
	v_add_f32_e32 v88, v88, v89
	ds_read_b128 v[60:63], v159 offset:10288
	v_add_f32_dpp v86, v86, v86 row_half_mirror row_mask:0xf bank_mask:0xf bound_ctrl:1
	v_add_f32_dpp v88, v88, v88 row_half_mirror row_mask:0xf bank_mask:0xf bound_ctrl:1
	ds_read_b128 v[80:83], v97 offset:160
	v_add_f32_dpp v86, v86, v86 quad_perm:[2,3,0,1] row_mask:0xf bank_mask:0xf bound_ctrl:1
	v_add_f32_dpp v88, v88, v88 quad_perm:[2,3,0,1] row_mask:0xf bank_mask:0xf bound_ctrl:1
	ds_read_b32 v84, v160 offset:17024
	v_add_f32_dpp v86, v86, v86 quad_perm:[1,0,3,2] row_mask:0xf bank_mask:0xf bound_ctrl:1
	v_add_f32_dpp v88, v88, v88 quad_perm:[1,0,3,2] row_mask:0xf bank_mask:0xf bound_ctrl:1
	v_fma_f32 v94, -v90, v86, v214
	v_mul_f32_e32 v95, v90, v88
	v_mul_f32_e32 v94, v211, v94
	v_cmp_eq_u32_e32 vcc, 1, v156
	v_mul_f32_e32 v92, v94, v91
	v_fma_f32 v96, v212, v94, v95
	v_pk_fma_f32 v[108:109], v[194:195], v[92:93], v[108:109] op_sel_hi:[1,0,1]
	v_pk_fma_f32 v[110:111], v[196:197], v[92:93], v[110:111] op_sel_hi:[1,0,1]
	v_cndmask_b32_e32 v36, v36, v96, vcc
	v_pk_fma_f32 v[112:113], v[198:199], v[92:93], v[112:113] op_sel_hi:[1,0,1]
	v_pk_fma_f32 v[114:115], v[200:201], v[92:93], v[114:115] op_sel_hi:[1,0,1]
	v_pk_fma_f32 v[116:117], v[202:203], v[92:93], v[116:117] op_sel_hi:[1,0,1]
	v_pk_fma_f32 v[118:119], v[204:205], v[92:93], v[118:119] op_sel_hi:[1,0,1]
	v_pk_fma_f32 v[120:121], v[206:207], v[92:93], v[120:121] op_sel_hi:[1,0,1]
	v_pk_fma_f32 v[122:123], v[208:209], v[92:93], v[122:123] op_sel_hi:[1,0,1]
	ds_read_b128 v[194:197], v159 offset:11776
	ds_read_b128 v[178:181], v159 offset:11264
	ds_read_b128 v[198:201], v159 offset:11792
	ds_read_b128 v[182:185], v159 offset:11280
	ds_read_b128 v[202:205], v159 offset:11808
	ds_read_b128 v[186:189], v159 offset:11296
	ds_read_b128 v[206:209], v159 offset:11824
	s_waitcnt lgkmcnt(7)
; __device__ __forceinline__ f32x2 fma2(f32x2 a, f32x2 b, f32x2 c) { return __builtin_elementwise_fma(a, b, c); }
; __device__ __forceinline__ float sum8(float x) { x += dppf<0x141>(x); x += dppf<0x4E>(x); x += dppf<0xB1>(x); return x; }
; template <int TB> __device__ __forceinline__ void gdn_block8(f32x2 (&S)[8], const LAS float* B, int kq, int vidx, float* oo) {
;     ...
;         for (int tt = 0; tt < SCAN_UNR; ++tt) {
;             const int t = t0 + tt;
;             const GOps8 n = g_ld8(B, (t + 1) & 15, kq, vidx);
;             const f32x2 k[8] = PAIRS8(c.k), q[8] = PAIRS8(c.q);
;             f32x2 pk = S[0] * k[0], pq = S[0] * q[0];
; #pragma unroll
;             for (int e = 1; e < 8; ++e) { pk = fma2(S[e], k[e], pk); pq = fma2(S[e], q[e], pq); }
;             const float dk = sum8(pk.x + pk.y), dq = sum8(pq.x + pq.y);
;             P *= c.sc.x; iP *= c.sc.w;
;             const float coef = c.sc.y * (c.v - P * dk);
;             const float cs = coef * iP; const f32x2 cf2 = {cs, cs};
; #pragma unroll
;             for (int e = 0; e < 8; ++e) S[e] = fma2(k[e], cf2, S[e]);
;             const float o = P * dq + c.sc.z * coef;
;             okA = (kq == t) ? o : okA; okB = (kq + 8 == t) ? o : okB;
;             c = n;
;         }
;         const f32x2 p2 = {P, P};
; #pragma unroll
;         for (int e = 0; e < 8; ++e) S[e] = S[e] * p2;
	v_pk_mul_f32 v[86:87], v[108:109], v[64:65]
	v_pk_mul_f32 v[88:89], v[108:109], v[48:49]
	v_pk_fma_f32 v[86:87], v[110:111], v[66:67], v[86:87]
	v_pk_fma_f32 v[88:89], v[110:111], v[50:51], v[88:89]
	v_pk_fma_f32 v[86:87], v[112:113], v[68:69], v[86:87]
	v_pk_fma_f32 v[88:89], v[112:113], v[52:53], v[88:89]
	v_mul_f32_e32 v90, v90, v80
	v_mul_f32_e32 v91, v91, v83
	v_pk_fma_f32 v[86:87], v[114:115], v[70:71], v[86:87]
	v_pk_fma_f32 v[88:89], v[114:115], v[54:55], v[88:89]
	v_pk_fma_f32 v[86:87], v[116:117], v[72:73], v[86:87]
	v_pk_fma_f32 v[88:89], v[116:117], v[56:57], v[88:89]
	v_pk_fma_f32 v[86:87], v[118:119], v[74:75], v[86:87]
	v_pk_fma_f32 v[88:89], v[118:119], v[58:59], v[88:89]
	v_pk_fma_f32 v[86:87], v[120:121], v[76:77], v[86:87]
	v_pk_fma_f32 v[88:89], v[120:121], v[60:61], v[88:89]
	v_pk_fma_f32 v[86:87], v[122:123], v[78:79], v[86:87]
	v_pk_fma_f32 v[88:89], v[122:123], v[62:63], v[88:89]
	v_add_f32_e32 v86, v86, v87
	v_add_f32_e32 v88, v88, v89
	ds_read_b128 v[190:193], v159 offset:11312
	v_add_f32_dpp v86, v86, v86 row_half_mirror row_mask:0xf bank_mask:0xf bound_ctrl:1
	v_add_f32_dpp v88, v88, v88 row_half_mirror row_mask:0xf bank_mask:0xf bound_ctrl:1
	ds_read_b128 v[210:213], v97 offset:176
	v_add_f32_dpp v86, v86, v86 quad_perm:[2,3,0,1] row_mask:0xf bank_mask:0xf bound_ctrl:1
	v_add_f32_dpp v88, v88, v88 quad_perm:[2,3,0,1] row_mask:0xf bank_mask:0xf bound_ctrl:1
	ds_read_b32 v214, v160 offset:17088
	v_add_f32_dpp v86, v86, v86 quad_perm:[1,0,3,2] row_mask:0xf bank_mask:0xf bound_ctrl:1
	v_add_f32_dpp v88, v88, v88 quad_perm:[1,0,3,2] row_mask:0xf bank_mask:0xf bound_ctrl:1
	v_fma_f32 v94, -v90, v86, v84
	v_mul_f32_e32 v95, v90, v88
	v_mul_f32_e32 v94, v81, v94
	v_cmp_eq_u32_e32 vcc, 2, v156
	v_mul_f32_e32 v92, v94, v91
	v_fma_f32 v96, v82, v94, v95
	v_pk_fma_f32 v[108:109], v[64:65], v[92:93], v[108:109] op_sel_hi:[1,0,1]
	v_pk_fma_f32 v[110:111], v[66:67], v[92:93], v[110:111] op_sel_hi:[1,0,1]
	v_cndmask_b32_e32 v36, v36, v96, vcc
	v_pk_fma_f32 v[112:113], v[68:69], v[92:93], v[112:113] op_sel_hi:[1,0,1]
	v_pk_fma_f32 v[114:115], v[70:71], v[92:93], v[114:115] op_sel_hi:[1,0,1]
	v_pk_fma_f32 v[116:117], v[72:73], v[92:93], v[116:117] op_sel_hi:[1,0,1]
	v_pk_fma_f32 v[118:119], v[74:75], v[92:93], v[118:119] op_sel_hi:[1,0,1]
	v_pk_fma_f32 v[120:121], v[76:77], v[92:93], v[120:121] op_sel_hi:[1,0,1]
	v_pk_fma_f32 v[122:123], v[78:79], v[92:93], v[122:123] op_sel_hi:[1,0,1]
	ds_read_b128 v[64:67], v159 offset:12800
	ds_read_b128 v[48:51], v159 offset:12288
	ds_read_b128 v[68:71], v159 offset:12816
	ds_read_b128 v[52:55], v159 offset:12304
	ds_read_b128 v[72:75], v159 offset:12832
	ds_read_b128 v[56:59], v159 offset:12320
	ds_read_b128 v[76:79], v159 offset:12848
	s_waitcnt lgkmcnt(7)
	v_pk_mul_f32 v[86:87], v[108:109], v[194:195]
	v_pk_mul_f32 v[88:89], v[108:109], v[178:179]
	v_pk_fma_f32 v[86:87], v[110:111], v[196:197], v[86:87]
	v_pk_fma_f32 v[88:89], v[110:111], v[180:181], v[88:89]
	v_pk_fma_f32 v[86:87], v[112:113], v[198:199], v[86:87]
	v_pk_fma_f32 v[88:89], v[112:113], v[182:183], v[88:89]
	v_mul_f32_e32 v90, v90, v210
	v_mul_f32_e32 v91, v91, v213
	v_pk_fma_f32 v[86:87], v[114:115], v[200:201], v[86:87]
	v_pk_fma_f32 v[88:89], v[114:115], v[184:185], v[88:89]
	v_pk_fma_f32 v[86:87], v[116:117], v[202:203], v[86:87]
	v_pk_fma_f32 v[88:89], v[116:117], v[186:187], v[88:89]
	v_pk_fma_f32 v[86:87], v[118:119], v[204:205], v[86:87]
	v_pk_fma_f32 v[88:89], v[118:119], v[188:189], v[88:89]
	v_pk_fma_f32 v[86:87], v[120:121], v[206:207], v[86:87]
	v_pk_fma_f32 v[88:89], v[120:121], v[190:191], v[88:89]
	v_pk_fma_f32 v[86:87], v[122:123], v[208:209], v[86:87]
	v_pk_fma_f32 v[88:89], v[122:123], v[192:193], v[88:89]
	v_add_f32_e32 v86, v86, v87
	v_add_f32_e32 v88, v88, v89
	ds_read_b128 v[60:63], v159 offset:12336
	v_add_f32_dpp v86, v86, v86 row_half_mirror row_mask:0xf bank_mask:0xf bound_ctrl:1
	v_add_f32_dpp v88, v88, v88 row_half_mirror row_mask:0xf bank_mask:0xf bound_ctrl:1
	ds_read_b128 v[80:83], v97 offset:192
	v_add_f32_dpp v86, v86, v86 quad_perm:[2,3,0,1] row_mask:0xf bank_mask:0xf bound_ctrl:1
	v_add_f32_dpp v88, v88, v88 quad_perm:[2,3,0,1] row_mask:0xf bank_mask:0xf bound_ctrl:1
	ds_read_b32 v84, v160 offset:17152
	v_add_f32_dpp v86, v86, v86 quad_perm:[1,0,3,2] row_mask:0xf bank_mask:0xf bound_ctrl:1
	v_add_f32_dpp v88, v88, v88 quad_perm:[1,0,3,2] row_mask:0xf bank_mask:0xf bound_ctrl:1
	v_fma_f32 v94, -v90, v86, v214
	v_mul_f32_e32 v95, v90, v88
	v_mul_f32_e32 v94, v211, v94
	v_cmp_eq_u32_e32 vcc, 3, v156
	v_mul_f32_e32 v92, v94, v91
	v_fma_f32 v96, v212, v94, v95
	v_pk_fma_f32 v[108:109], v[194:195], v[92:93], v[108:109] op_sel_hi:[1,0,1]
	v_pk_fma_f32 v[110:111], v[196:197], v[92:93], v[110:111] op_sel_hi:[1,0,1]
	v_cndmask_b32_e32 v36, v36, v96, vcc
	v_pk_fma_f32 v[112:113], v[198:199], v[92:93], v[112:113] op_sel_hi:[1,0,1]
	v_pk_fma_f32 v[114:115], v[200:201], v[92:93], v[114:115] op_sel_hi:[1,0,1]
	v_pk_fma_f32 v[116:117], v[202:203], v[92:93], v[116:117] op_sel_hi:[1,0,1]
	v_pk_fma_f32 v[118:119], v[204:205], v[92:93], v[118:119] op_sel_hi:[1,0,1]
	v_pk_fma_f32 v[120:121], v[206:207], v[92:93], v[120:121] op_sel_hi:[1,0,1]
	v_pk_fma_f32 v[122:123], v[208:209], v[92:93], v[122:123] op_sel_hi:[1,0,1]
	v_pk_mul_f32 v[108:109], v[90:91], v[108:109] op_sel_hi:[0,1]
	v_pk_mul_f32 v[110:111], v[90:91], v[110:111] op_sel_hi:[0,1]
	v_pk_mul_f32 v[112:113], v[90:91], v[112:113] op_sel_hi:[0,1]
	v_pk_mul_f32 v[114:115], v[90:91], v[114:115] op_sel_hi:[0,1]
	v_pk_mul_f32 v[116:117], v[90:91], v[116:117] op_sel_hi:[0,1]
	v_pk_mul_f32 v[118:119], v[90:91], v[118:119] op_sel_hi:[0,1]
	v_pk_mul_f32 v[120:121], v[90:91], v[120:121] op_sel_hi:[0,1]
	v_pk_mul_f32 v[122:123], v[90:91], v[122:123] op_sel_hi:[0,1]
	ds_read_b128 v[194:197], v159 offset:13824
	ds_read_b128 v[178:181], v159 offset:13312
	ds_read_b128 v[198:201], v159 offset:13840
	ds_read_b128 v[182:185], v159 offset:13328
	ds_read_b128 v[202:205], v159 offset:13856
	ds_read_b128 v[186:189], v159 offset:13344
	ds_read_b128 v[206:209], v159 offset:13872
	s_waitcnt lgkmcnt(7)
; __device__ __forceinline__ f32x2 fma2(f32x2 a, f32x2 b, f32x2 c) { return __builtin_elementwise_fma(a, b, c); }
; __device__ __forceinline__ float sum8(float x) { x += dppf<0x141>(x); x += dppf<0x4E>(x); x += dppf<0xB1>(x); return x; }
; template <int TB> __device__ __forceinline__ void gdn_block8(f32x2 (&S)[8], const LAS float* B, int kq, int vidx, float* oo) {
;     ...
;         for (int tt = 0; tt < SCAN_UNR; ++tt) {
;             const int t = t0 + tt;
;             const GOps8 n = g_ld8(B, (t + 1) & 15, kq, vidx);
;             const f32x2 k[8] = PAIRS8(c.k), q[8] = PAIRS8(c.q);
;             f32x2 pk = S[0] * k[0], pq = S[0] * q[0];
; #pragma unroll
;             for (int e = 1; e < 8; ++e) { pk = fma2(S[e], k[e], pk); pq = fma2(S[e], q[e], pq); }
;             const float dk = sum8(pk.x + pk.y), dq = sum8(pq.x + pq.y);
;             P *= c.sc.x; iP *= c.sc.w;
;             const float coef = c.sc.y * (c.v - P * dk);
;             const float cs = coef * iP; const f32x2 cf2 = {cs, cs};
; #pragma unroll
;             for (int e = 0; e < 8; ++e) S[e] = fma2(k[e], cf2, S[e]);
;             const float o = P * dq + c.sc.z * coef;
;             okA = (kq == t) ? o : okA; okB = (kq + 8 == t) ? o : okB;
;             c = n;
;         }
	v_pk_mul_f32 v[86:87], v[108:109], v[64:65]
	v_pk_mul_f32 v[88:89], v[108:109], v[48:49]
	v_pk_fma_f32 v[86:87], v[110:111], v[66:67], v[86:87]
	v_pk_fma_f32 v[88:89], v[110:111], v[50:51], v[88:89]
	v_pk_fma_f32 v[86:87], v[112:113], v[68:69], v[86:87]
	v_pk_fma_f32 v[88:89], v[112:113], v[52:53], v[88:89]
	v_pk_fma_f32 v[86:87], v[114:115], v[70:71], v[86:87]
	v_pk_fma_f32 v[88:89], v[114:115], v[54:55], v[88:89]
	v_pk_fma_f32 v[86:87], v[116:117], v[72:73], v[86:87]
	v_pk_fma_f32 v[88:89], v[116:117], v[56:57], v[88:89]
	v_pk_fma_f32 v[86:87], v[118:119], v[74:75], v[86:87]
	v_pk_fma_f32 v[88:89], v[118:119], v[58:59], v[88:89]
	v_pk_fma_f32 v[86:87], v[120:121], v[76:77], v[86:87]
	v_pk_fma_f32 v[88:89], v[120:121], v[60:61], v[88:89]
	v_pk_fma_f32 v[86:87], v[122:123], v[78:79], v[86:87]
	v_pk_fma_f32 v[88:89], v[122:123], v[62:63], v[88:89]
	v_add_f32_e32 v86, v86, v87
	v_add_f32_e32 v88, v88, v89
	ds_read_b128 v[190:193], v159 offset:13360
	v_add_f32_dpp v86, v86, v86 row_half_mirror row_mask:0xf bank_mask:0xf bound_ctrl:1
	v_add_f32_dpp v88, v88, v88 row_half_mirror row_mask:0xf bank_mask:0xf bound_ctrl:1
	ds_read_b128 v[210:213], v97 offset:208
	v_add_f32_dpp v86, v86, v86 quad_perm:[2,3,0,1] row_mask:0xf bank_mask:0xf bound_ctrl:1
	v_add_f32_dpp v88, v88, v88 quad_perm:[2,3,0,1] row_mask:0xf bank_mask:0xf bound_ctrl:1
	ds_read_b32 v214, v160 offset:17216
	v_add_f32_dpp v86, v86, v86 quad_perm:[1,0,3,2] row_mask:0xf bank_mask:0xf bound_ctrl:1
	v_add_f32_dpp v88, v88, v88 quad_perm:[1,0,3,2] row_mask:0xf bank_mask:0xf bound_ctrl:1
	v_fma_f32 v94, -v80, v86, v84
	v_mul_f32_e32 v95, v80, v88
	v_mul_f32_e32 v94, v81, v94
	v_cmp_eq_u32_e32 vcc, 4, v156
	v_mul_f32_e32 v92, v94, v83
	v_fma_f32 v96, v82, v94, v95
	v_pk_fma_f32 v[108:109], v[64:65], v[92:93], v[108:109] op_sel_hi:[1,0,1]
	v_pk_fma_f32 v[110:111], v[66:67], v[92:93], v[110:111] op_sel_hi:[1,0,1]
	v_cndmask_b32_e32 v36, v36, v96, vcc
	v_pk_fma_f32 v[112:113], v[68:69], v[92:93], v[112:113] op_sel_hi:[1,0,1]
	v_pk_fma_f32 v[114:115], v[70:71], v[92:93], v[114:115] op_sel_hi:[1,0,1]
	v_pk_fma_f32 v[116:117], v[72:73], v[92:93], v[116:117] op_sel_hi:[1,0,1]
	v_pk_fma_f32 v[118:119], v[74:75], v[92:93], v[118:119] op_sel_hi:[1,0,1]
	v_pk_fma_f32 v[120:121], v[76:77], v[92:93], v[120:121] op_sel_hi:[1,0,1]
	v_pk_fma_f32 v[122:123], v[78:79], v[92:93], v[122:123] op_sel_hi:[1,0,1]
	ds_read_b128 v[64:67], v159 offset:14848
	ds_read_b128 v[48:51], v159 offset:14336
	ds_read_b128 v[68:71], v159 offset:14864
	ds_read_b128 v[52:55], v159 offset:14352
	ds_read_b128 v[72:75], v159 offset:14880
	ds_read_b128 v[56:59], v159 offset:14368
	ds_read_b128 v[76:79], v159 offset:14896
	s_waitcnt lgkmcnt(7)
	v_pk_mul_f32 v[86:87], v[108:109], v[194:195]
	v_pk_mul_f32 v[88:89], v[108:109], v[178:179]
	v_pk_fma_f32 v[86:87], v[110:111], v[196:197], v[86:87]
	v_pk_fma_f32 v[88:89], v[110:111], v[180:181], v[88:89]
	v_pk_fma_f32 v[86:87], v[112:113], v[198:199], v[86:87]
	v_pk_fma_f32 v[88:89], v[112:113], v[182:183], v[88:89]
	v_mul_f32_e32 v90, v80, v210
	v_mul_f32_e32 v91, v83, v213
	v_pk_fma_f32 v[86:87], v[114:115], v[200:201], v[86:87]
	v_pk_fma_f32 v[88:89], v[114:115], v[184:185], v[88:89]
	v_pk_fma_f32 v[86:87], v[116:117], v[202:203], v[86:87]
	v_pk_fma_f32 v[88:89], v[116:117], v[186:187], v[88:89]
	v_pk_fma_f32 v[86:87], v[118:119], v[204:205], v[86:87]
	v_pk_fma_f32 v[88:89], v[118:119], v[188:189], v[88:89]
	v_pk_fma_f32 v[86:87], v[120:121], v[206:207], v[86:87]
	v_pk_fma_f32 v[88:89], v[120:121], v[190:191], v[88:89]
	v_pk_fma_f32 v[86:87], v[122:123], v[208:209], v[86:87]
	v_pk_fma_f32 v[88:89], v[122:123], v[192:193], v[88:89]
	v_add_f32_e32 v86, v86, v87
	v_add_f32_e32 v88, v88, v89
	ds_read_b128 v[60:63], v159 offset:14384
	v_add_f32_dpp v86, v86, v86 row_half_mirror row_mask:0xf bank_mask:0xf bound_ctrl:1
	v_add_f32_dpp v88, v88, v88 row_half_mirror row_mask:0xf bank_mask:0xf bound_ctrl:1
	ds_read_b128 v[80:83], v97 offset:224
	v_add_f32_dpp v86, v86, v86 quad_perm:[2,3,0,1] row_mask:0xf bank_mask:0xf bound_ctrl:1
	v_add_f32_dpp v88, v88, v88 quad_perm:[2,3,0,1] row_mask:0xf bank_mask:0xf bound_ctrl:1
	ds_read_b32 v84, v160 offset:17280
	v_add_f32_dpp v86, v86, v86 quad_perm:[1,0,3,2] row_mask:0xf bank_mask:0xf bound_ctrl:1
	v_add_f32_dpp v88, v88, v88 quad_perm:[1,0,3,2] row_mask:0xf bank_mask:0xf bound_ctrl:1
	v_fma_f32 v94, -v90, v86, v214
	v_mul_f32_e32 v95, v90, v88
	v_mul_f32_e32 v94, v211, v94
	v_cmp_eq_u32_e32 vcc, 5, v156
	v_mul_f32_e32 v92, v94, v91
	v_fma_f32 v96, v212, v94, v95
	v_pk_fma_f32 v[108:109], v[194:195], v[92:93], v[108:109] op_sel_hi:[1,0,1]
	v_pk_fma_f32 v[110:111], v[196:197], v[92:93], v[110:111] op_sel_hi:[1,0,1]
	v_cndmask_b32_e32 v36, v36, v96, vcc
	v_pk_fma_f32 v[112:113], v[198:199], v[92:93], v[112:113] op_sel_hi:[1,0,1]
	v_pk_fma_f32 v[114:115], v[200:201], v[92:93], v[114:115] op_sel_hi:[1,0,1]
	v_pk_fma_f32 v[116:117], v[202:203], v[92:93], v[116:117] op_sel_hi:[1,0,1]
	v_pk_fma_f32 v[118:119], v[204:205], v[92:93], v[118:119] op_sel_hi:[1,0,1]
	v_pk_fma_f32 v[120:121], v[206:207], v[92:93], v[120:121] op_sel_hi:[1,0,1]
	v_pk_fma_f32 v[122:123], v[208:209], v[92:93], v[122:123] op_sel_hi:[1,0,1]
	ds_read_b128 v[194:197], v159 offset:15872
	ds_read_b128 v[178:181], v159 offset:15360
	ds_read_b128 v[198:201], v159 offset:15888
	ds_read_b128 v[182:185], v159 offset:15376
	ds_read_b128 v[202:205], v159 offset:15904
	ds_read_b128 v[186:189], v159 offset:15392
	ds_read_b128 v[206:209], v159 offset:15920
	s_waitcnt lgkmcnt(7)
; template <int TB> __device__ __forceinline__ void gdn_block8(f32x2 (&S)[8], const LAS float* B, int kq, int vidx, float* oo) {
;     ...
;         for (int tt = 0; tt < SCAN_UNR; ++tt) {
;             const int t = t0 + tt;
;             const GOps8 n = g_ld8(B, (t + 1) & 15, kq, vidx);
;             const f32x2 k[8] = PAIRS8(c.k), q[8] = PAIRS8(c.q);
;             f32x2 pk = S[0] * k[0], pq = S[0] * q[0];
; #pragma unroll
;             for (int e = 1; e < 8; ++e) { pk = fma2(S[e], k[e], pk); pq = fma2(S[e], q[e], pq); }
;             const float dk = sum8(pk.x + pk.y), dq = sum8(pq.x + pq.y);
;             P *= c.sc.x; iP *= c.sc.w;
;             const float coef = c.sc.y * (c.v - P * dk);
;             const float cs = coef * iP; const f32x2 cf2 = {cs, cs};
; #pragma unroll
;             for (int e = 0; e < 8; ++e) S[e] = fma2(k[e], cf2, S[e]);
;             const float o = P * dq + c.sc.z * coef;
;             okA = (kq == t) ? o : okA; okB = (kq + 8 == t) ? o : okB;
;             c = n;
;         }
;         const f32x2 p2 = {P, P};
; #pragma unroll
;         for (int e = 0; e < 8; ++e) S[e] = S[e] * p2;
;     }
;     oo[(size_t)kq * GW] = okA;
;     if (TB == 16) oo[(size_t)(kq + 8) * GW] = okB;
; __device__ __forceinline__ void phase_scan(Ctx& C, int i) {
;     ...
;         for (int blk = 0; blk < SC_NBLK; ++blk) {
;             RELAUNDER;
;             G_DESC(blk, m0, tb, head, cgp, b, isprompt)
;             const bool last = isprompt ? (blk == 127) : true;
;             if (blk + 1 < SC_NBLK) G_STAGE_LOAD(blk + 1);
;             const LAS float* B = buf0 + (blk & 1) * GBUF;
;             const int col = cgp * 16 + w * 8 + sub;
;             float* oo = ORAW + m0 * GW + head * 128 + col;
;             if (cw) {
;             if (tb == 16) gdn_block8<16>(S, B, kq, w * 8 + sub, oo); else gdn_block8<8>(S, B, kq, w * 8 + sub, oo);
;             if (last) {
;                 float* So = (isprompt ? C.out + O_GDN_P + ((size_t)(i * NB + b) * GH + head) * 16384 : C.out + O_GDN_S + ((size_t)(i * SB + b) * GH + head) * 16384) + col;
; #pragma unroll
;                 for (int e = 0; e < 8; ++e) { So[(size_t)(kq * 16 + 2 * e) * 128] = S[e].x; So[(size_t)(kq * 16 + 2 * e + 1) * 128] = S[e].y; S[e] = (f32x2){Snext[2 * e], Snext[2 * e + 1]}; }
;             }
;             }
;             if (blk + 1 < SC_NBLK) G_STAGE_WRITE(blk + 1);
;             __syncthreads();
	v_pk_mul_f32 v[86:87], v[108:109], v[64:65]
	v_pk_mul_f32 v[88:89], v[108:109], v[48:49]
	v_pk_fma_f32 v[86:87], v[110:111], v[66:67], v[86:87]
	v_pk_fma_f32 v[88:89], v[110:111], v[50:51], v[88:89]
	v_pk_fma_f32 v[86:87], v[112:113], v[68:69], v[86:87]
	v_pk_fma_f32 v[88:89], v[112:113], v[52:53], v[88:89]
	v_mul_f32_e32 v90, v90, v80
	v_mul_f32_e32 v91, v91, v83
	v_pk_fma_f32 v[86:87], v[114:115], v[70:71], v[86:87]
	v_pk_fma_f32 v[88:89], v[114:115], v[54:55], v[88:89]
	v_pk_fma_f32 v[86:87], v[116:117], v[72:73], v[86:87]
	v_pk_fma_f32 v[88:89], v[116:117], v[56:57], v[88:89]
	v_pk_fma_f32 v[86:87], v[118:119], v[74:75], v[86:87]
	v_pk_fma_f32 v[88:89], v[118:119], v[58:59], v[88:89]
	v_pk_fma_f32 v[86:87], v[120:121], v[76:77], v[86:87]
	v_pk_fma_f32 v[88:89], v[120:121], v[60:61], v[88:89]
	v_pk_fma_f32 v[86:87], v[122:123], v[78:79], v[86:87]
	v_pk_fma_f32 v[88:89], v[122:123], v[62:63], v[88:89]
	v_add_f32_e32 v86, v86, v87
	v_add_f32_e32 v88, v88, v89
	ds_read_b128 v[190:193], v159 offset:15408
	v_add_f32_dpp v86, v86, v86 row_half_mirror row_mask:0xf bank_mask:0xf bound_ctrl:1
	v_add_f32_dpp v88, v88, v88 row_half_mirror row_mask:0xf bank_mask:0xf bound_ctrl:1
	ds_read_b128 v[210:213], v97 offset:240
	v_add_f32_dpp v86, v86, v86 quad_perm:[2,3,0,1] row_mask:0xf bank_mask:0xf bound_ctrl:1
	v_add_f32_dpp v88, v88, v88 quad_perm:[2,3,0,1] row_mask:0xf bank_mask:0xf bound_ctrl:1
	ds_read_b32 v214, v160 offset:17344
	v_add_f32_dpp v86, v86, v86 quad_perm:[1,0,3,2] row_mask:0xf bank_mask:0xf bound_ctrl:1
	v_add_f32_dpp v88, v88, v88 quad_perm:[1,0,3,2] row_mask:0xf bank_mask:0xf bound_ctrl:1
	v_fma_f32 v94, -v90, v86, v84
	v_mul_f32_e32 v95, v90, v88
	v_mul_f32_e32 v94, v81, v94
	v_cmp_eq_u32_e32 vcc, 6, v156
	v_mul_f32_e32 v92, v94, v91
	v_fma_f32 v96, v82, v94, v95
	v_pk_fma_f32 v[108:109], v[64:65], v[92:93], v[108:109] op_sel_hi:[1,0,1]
	v_pk_fma_f32 v[110:111], v[66:67], v[92:93], v[110:111] op_sel_hi:[1,0,1]
	v_cndmask_b32_e32 v36, v36, v96, vcc
	v_pk_fma_f32 v[112:113], v[68:69], v[92:93], v[112:113] op_sel_hi:[1,0,1]
	v_pk_fma_f32 v[114:115], v[70:71], v[92:93], v[114:115] op_sel_hi:[1,0,1]
	v_pk_fma_f32 v[116:117], v[72:73], v[92:93], v[116:117] op_sel_hi:[1,0,1]
	v_pk_fma_f32 v[118:119], v[74:75], v[92:93], v[118:119] op_sel_hi:[1,0,1]
	v_pk_fma_f32 v[120:121], v[76:77], v[92:93], v[120:121] op_sel_hi:[1,0,1]
	v_pk_fma_f32 v[122:123], v[78:79], v[92:93], v[122:123] op_sel_hi:[1,0,1]
	s_waitcnt lgkmcnt(0)
	v_pk_mul_f32 v[86:87], v[108:109], v[194:195]
	v_pk_mul_f32 v[88:89], v[108:109], v[178:179]
	v_pk_fma_f32 v[86:87], v[110:111], v[196:197], v[86:87]
	v_pk_fma_f32 v[88:89], v[110:111], v[180:181], v[88:89]
	v_pk_fma_f32 v[86:87], v[112:113], v[198:199], v[86:87]
	v_pk_fma_f32 v[88:89], v[112:113], v[182:183], v[88:89]
	v_mul_f32_e32 v90, v90, v210
	v_mul_f32_e32 v91, v91, v213
	v_pk_fma_f32 v[86:87], v[114:115], v[200:201], v[86:87]
	v_pk_fma_f32 v[88:89], v[114:115], v[184:185], v[88:89]
	v_pk_fma_f32 v[86:87], v[116:117], v[202:203], v[86:87]
	v_pk_fma_f32 v[88:89], v[116:117], v[186:187], v[88:89]
	v_pk_fma_f32 v[86:87], v[118:119], v[204:205], v[86:87]
	v_pk_fma_f32 v[88:89], v[118:119], v[188:189], v[88:89]
	v_pk_fma_f32 v[86:87], v[120:121], v[206:207], v[86:87]
	v_pk_fma_f32 v[88:89], v[120:121], v[190:191], v[88:89]
	v_pk_fma_f32 v[86:87], v[122:123], v[208:209], v[86:87]
	v_pk_fma_f32 v[88:89], v[122:123], v[192:193], v[88:89]
	v_add_f32_e32 v86, v86, v87
	v_add_f32_e32 v88, v88, v89
	s_nop 0
	v_add_f32_dpp v86, v86, v86 row_half_mirror row_mask:0xf bank_mask:0xf bound_ctrl:1
	v_add_f32_dpp v88, v88, v88 row_half_mirror row_mask:0xf bank_mask:0xf bound_ctrl:1
	s_nop 0
	v_add_f32_dpp v86, v86, v86 quad_perm:[2,3,0,1] row_mask:0xf bank_mask:0xf bound_ctrl:1
	v_add_f32_dpp v88, v88, v88 quad_perm:[2,3,0,1] row_mask:0xf bank_mask:0xf bound_ctrl:1
	s_nop 0
	v_add_f32_dpp v86, v86, v86 quad_perm:[1,0,3,2] row_mask:0xf bank_mask:0xf bound_ctrl:1
	v_add_f32_dpp v88, v88, v88 quad_perm:[1,0,3,2] row_mask:0xf bank_mask:0xf bound_ctrl:1
	v_fma_f32 v94, -v90, v86, v214
	v_mul_f32_e32 v95, v90, v88
	v_mul_f32_e32 v94, v211, v94
	v_cmp_eq_u32_e32 vcc, 7, v156
	v_mul_f32_e32 v92, v94, v91
	v_fma_f32 v96, v212, v94, v95
	v_pk_fma_f32 v[108:109], v[194:195], v[92:93], v[108:109] op_sel_hi:[1,0,1]
	v_pk_fma_f32 v[110:111], v[196:197], v[92:93], v[110:111] op_sel_hi:[1,0,1]
	v_cndmask_b32_e32 v36, v36, v96, vcc
	v_pk_fma_f32 v[112:113], v[198:199], v[92:93], v[112:113] op_sel_hi:[1,0,1]
	v_pk_fma_f32 v[114:115], v[200:201], v[92:93], v[114:115] op_sel_hi:[1,0,1]
	v_pk_fma_f32 v[116:117], v[202:203], v[92:93], v[116:117] op_sel_hi:[1,0,1]
	v_pk_fma_f32 v[118:119], v[204:205], v[92:93], v[118:119] op_sel_hi:[1,0,1]
	v_pk_fma_f32 v[120:121], v[206:207], v[92:93], v[120:121] op_sel_hi:[1,0,1]
	v_pk_fma_f32 v[122:123], v[208:209], v[92:93], v[122:123] op_sel_hi:[1,0,1]
	v_pk_mul_f32 v[108:109], v[90:91], v[108:109] op_sel_hi:[0,1]
	v_pk_mul_f32 v[110:111], v[90:91], v[110:111] op_sel_hi:[0,1]
	v_pk_mul_f32 v[112:113], v[90:91], v[112:113] op_sel_hi:[0,1]
	v_pk_mul_f32 v[114:115], v[90:91], v[114:115] op_sel_hi:[0,1]
	v_pk_mul_f32 v[116:117], v[90:91], v[116:117] op_sel_hi:[0,1]
	v_pk_mul_f32 v[118:119], v[90:91], v[118:119] op_sel_hi:[0,1]
	v_pk_mul_f32 v[120:121], v[90:91], v[120:121] op_sel_hi:[0,1]
	v_pk_mul_f32 v[122:123], v[90:91], v[122:123] op_sel_hi:[0,1]
	s_cmpk_gt_u32 s29, 0x7e
	s_cbranch_scc1 .Lgdn16_exit
	v_lshlrev_b32_e32 v28, 11, v156
	v_mov_b32_e32 v29, v3
	v_lshl_add_u64 v[30:31], v[0:1], 0, v[28:29]
	global_store_dword v[30:31], v37, off
	s_mov_b32 s4, 0x4000
	s_mov_b32 s5, 0
	v_lshl_add_u64 v[30:31], v[30:31], 0, s[4:5]
	global_store_dword v[30:31], v36, off
	s_mov_b32 s4, 0x8000
	v_lshl_add_u64 v[0:1], v[0:1], 0, s[4:5]
	s_add_i32 s29, s29, 1
	s_xor_b32 s2, s2, 0x4500
	v_add_u32_e32 v157, s2, v162
	s_lshl_b32 s4, s59, 2
	s_add_i32 s4, s2, s4
	v_lshl_add_u32 v158, v161, 2, s4
	v_add_u32_e32 v159, 0xa900, v157
	v_add_u32_e32 v160, 0xa900, v158
	s_add_i32 s48, s2, 0xed00
	v_mov_b32_e32 v37, 0
	v_mov_b32_e32 v36, 0
	s_waitcnt lgkmcnt(0)
	s_barrier
	s_branch .Lgdn16_top
.Lgdn16_exit:
	v_lshlrev_b32_e32 v28, 11, v156
	v_mov_b32_e32 v29, v3
	v_lshl_add_u64 v[0:1], v[0:1], 0, v[28:29]
	global_store_dword v[0:1], v37, off
	v_add_co_u32_e32 v0, vcc, 0x4000, v0
	v_mov_b32_e32 v29, v123
	s_nop 0
	v_addc_co_u32_e32 v1, vcc, 0, v1, vcc
	global_store_dword v[0:1], v36, off
	v_mov_b32_e32 v28, v122
	v_mov_b32_e32 v31, v121
	v_mov_b32_e32 v30, v120
	v_mov_b32_e32 v33, v119
	v_mov_b32_e32 v32, v118
	v_mov_b32_e32 v35, v117
	v_mov_b32_e32 v34, v116
	v_mov_b32_e32 v37, v115
	v_mov_b32_e32 v36, v114
	v_mov_b32_e32 v39, v113
	v_mov_b32_e32 v38, v112
	v_mov_b32_e32 v41, v111
	v_mov_b32_e32 v40, v110
	v_mov_b32_e32 v43, v109
	v_mov_b32_e32 v42, v108
	s_andn2_b64 vcc, exec, s[46:47]
	s_cbranch_vccz .LBB0_970
	s_branch .LBB0_971

; #define LAS __attribute__((address_space(3)))
; __device__ __forceinline__ f32x2 fma2(f32x2 a, f32x2 b, f32x2 c) { return __builtin_elementwise_fma(a, b, c); }
; __device__ __forceinline__ float sum8(float x) { x += dppf<0x141>(x); x += dppf<0x4E>(x); x += dppf<0xB1>(x); return x; }
; __device__ __forceinline__ ROps8 r_ld8(const LAS float* B, int t, int kq, int vidx) {
;     ROps8 o; const LAS float* V = B + t * 320 + kq * 8;
; #pragma unroll
;     for (int h = 0; h < 2; ++h) { o.u[h] = *(const LAS f32x4*)(V + 4 * h); o.a[h] = *(const LAS f32x4*)(V + 64 + 4 * h); o.b[h] = *(const LAS f32x4*)(V + 128 + 4 * h); o.k[h] = *(const LAS f32x4*)(V + 192 + 4 * h); o.w[h] = *(const LAS f32x4*)(V + 256 + 4 * h); }
;     o.v = B[5120 + t * 16 + vidx]; o.sc = *(const LAS f32x2*)(B + 5376 + t * 2); return o;
; }
; template <int TB> __device__ __forceinline__ void rwkv_block8(f32x2 (&S)[4], const LAS float* B, int kq, int vidx, float* yo) {
;     float ykA = 0.f, ykB = 0.f;
;     ROps8 c = r_ld8(B, 0, kq, vidx);
; #pragma unroll 1
;     for (int t0 = 0; t0 < TB; t0 += SCAN_UNR)
; #pragma unroll
;     for (int tt = 0; tt < SCAN_UNR; ++tt) {
;         const int t = t0 + tt;
;         const ROps8 n = r_ld8(B, (t + 1) & 15, kq, vidx);
;         const f32x2 a[4] = PAIRS(c.a), w[4] = PAIRS(c.w), u[4] = PAIRS(c.u), b[4] = PAIRS(c.b), k[4] = PAIRS(c.k);
;         const f32x2 ps = fma2(S[3], a[3], fma2(S[2], a[2], fma2(S[1], a[1], S[0] * a[0]))), py = fma2(S[3], w[3], fma2(S[2], w[2], fma2(S[1], w[1], S[0] * w[0])));
;         const float sa = sum8(ps.x + ps.y), yp = sum8(py.x + py.y);
;         const f32x2 sa2 = {sa, sa}, v2 = {c.v, c.v};
; #pragma unroll
;         for (int e = 0; e < 4; ++e) { S[e] = fma2(-u[e], S[e], S[e]); S[e] = fma2(sa2, b[e], S[e]); S[e] = fma2(v2, k[e], S[e]); }
;         const float y = yp + sa * c.sc.x + c.v * c.sc.y;
;         ykA = (kq == t) ? y : ykA; ykB = (kq + 8 == t) ? y : ykB;
;         c = n;
;     }
.LBB0_1054:
.Lrwkv16_top:
	v_mov_b32_e32 v56, s49
	ds_read_b128 v[82:85], v145 offset:256
	ds_read_b128 v[86:89], v145 offset:272
	ds_read_b128 v[106:109], v145 offset:1024
	ds_read_b128 v[110:113], v145 offset:1040
	ds_read_b64 v[114:115], v56 offset:0
	ds_read_b32 v116, v146 offset:20480
	ds_read_b128 v[74:77], v145 offset:0
	ds_read_b128 v[78:81], v145 offset:16
	ds_read_b128 v[90:93], v145 offset:512
	ds_read_b128 v[94:97], v145 offset:528
	ds_read_b128 v[98:101], v145 offset:768
	ds_read_b128 v[102:105], v145 offset:784
	ds_read_b128 v[186:189], v145 offset:1536
	ds_read_b128 v[190:193], v145 offset:1552
	ds_read_b128 v[210:213], v145 offset:2304
	ds_read_b128 v[214:217], v145 offset:2320
	ds_read_b64 v[218:219], v56 offset:8
	ds_read_b32 v220, v146 offset:20544
	ds_read_b128 v[178:181], v145 offset:1280
	ds_read_b128 v[182:185], v145 offset:1296
	ds_read_b128 v[194:197], v145 offset:1792
	s_waitcnt lgkmcnt(9)
	v_pk_mul_f32 v[50:51], v[120:121], v[82:83]
	v_pk_mul_f32 v[52:53], v[120:121], v[106:107]
	v_pk_fma_f32 v[50:51], v[122:123], v[84:85], v[50:51]
	v_pk_fma_f32 v[52:53], v[122:123], v[108:109], v[52:53]
	v_pk_fma_f32 v[50:51], v[124:125], v[86:87], v[50:51]
	v_pk_fma_f32 v[52:53], v[124:125], v[110:111], v[52:53]
	v_pk_fma_f32 v[50:51], v[126:127], v[88:89], v[50:51]
	v_pk_fma_f32 v[52:53], v[126:127], v[112:113], v[52:53]
	v_add_f32_e32 v50, v50, v51
	v_add_f32_e32 v52, v52, v53
	ds_read_b128 v[198:201], v145 offset:1808
	v_add_f32_dpp v50, v50, v50 row_half_mirror row_mask:0xf bank_mask:0xf bound_ctrl:1
	v_add_f32_dpp v52, v52, v52 row_half_mirror row_mask:0xf bank_mask:0xf bound_ctrl:1
	ds_read_b128 v[202:205], v145 offset:2048
	v_add_f32_dpp v50, v50, v50 quad_perm:[2,3,0,1] row_mask:0xf bank_mask:0xf bound_ctrl:1
	v_add_f32_dpp v52, v52, v52 quad_perm:[2,3,0,1] row_mask:0xf bank_mask:0xf bound_ctrl:1
	ds_read_b128 v[206:209], v145 offset:2064
	v_add_f32_dpp v50, v50, v50 quad_perm:[1,0,3,2] row_mask:0xf bank_mask:0xf bound_ctrl:1
	v_add_f32_dpp v52, v52, v52 quad_perm:[1,0,3,2] row_mask:0xf bank_mask:0xf bound_ctrl:1
	v_pk_fma_f32 v[120:121], v[74:75], v[120:121], v[120:121] neg_lo:[1,0,0] neg_hi:[1,0,0]
	v_pk_fma_f32 v[122:123], v[76:77], v[122:123], v[122:123] neg_lo:[1,0,0] neg_hi:[1,0,0]
	v_pk_fma_f32 v[124:125], v[78:79], v[124:125], v[124:125] neg_lo:[1,0,0] neg_hi:[1,0,0]
	v_pk_fma_f32 v[126:127], v[80:81], v[126:127], v[126:127] neg_lo:[1,0,0] neg_hi:[1,0,0]
	v_cmp_eq_u32_e32 vcc, 0, v129
	v_pk_fma_f32 v[120:121], v[50:51], v[90:91], v[120:121] op_sel_hi:[0,1,1]
	v_fma_f32 v54, v50, v114, v52
	v_pk_fma_f32 v[122:123], v[50:51], v[92:93], v[122:123] op_sel_hi:[0,1,1]
	v_pk_fma_f32 v[124:125], v[50:51], v[94:95], v[124:125] op_sel_hi:[0,1,1]
	v_pk_fma_f32 v[126:127], v[50:51], v[96:97], v[126:127] op_sel_hi:[0,1,1]
	v_fma_f32 v55, v116, v115, v54
	v_pk_fma_f32 v[120:121], v[116:117], v[98:99], v[120:121] op_sel_hi:[0,1,1]
	v_pk_fma_f32 v[122:123], v[116:117], v[100:101], v[122:123] op_sel_hi:[0,1,1]
	v_cndmask_b32_e32 v49, v49, v55, vcc
	v_pk_fma_f32 v[124:125], v[116:117], v[102:103], v[124:125] op_sel_hi:[0,1,1]
	v_pk_fma_f32 v[126:127], v[116:117], v[104:105], v[126:127] op_sel_hi:[0,1,1]
	ds_read_b128 v[82:85], v145 offset:2816
	ds_read_b128 v[86:89], v145 offset:2832
	ds_read_b128 v[106:109], v145 offset:3584
	ds_read_b128 v[110:113], v145 offset:3600
	ds_read_b64 v[114:115], v56 offset:16
	ds_read_b32 v116, v146 offset:20608
	ds_read_b128 v[74:77], v145 offset:2560
	ds_read_b128 v[78:81], v145 offset:2576
	ds_read_b128 v[90:93], v145 offset:3072
	s_waitcnt lgkmcnt(9)
	v_pk_mul_f32 v[50:51], v[120:121], v[186:187]
	v_pk_mul_f32 v[52:53], v[120:121], v[210:211]
	v_pk_fma_f32 v[50:51], v[122:123], v[188:189], v[50:51]
	v_pk_fma_f32 v[52:53], v[122:123], v[212:213], v[52:53]
	v_pk_fma_f32 v[50:51], v[124:125], v[190:191], v[50:51]
	v_pk_fma_f32 v[52:53], v[124:125], v[214:215], v[52:53]
	v_pk_fma_f32 v[50:51], v[126:127], v[192:193], v[50:51]
	v_pk_fma_f32 v[52:53], v[126:127], v[216:217], v[52:53]
	v_add_f32_e32 v50, v50, v51
	v_add_f32_e32 v52, v52, v53
	ds_read_b128 v[94:97], v145 offset:3088
	v_add_f32_dpp v50, v50, v50 row_half_mirror row_mask:0xf bank_mask:0xf bound_ctrl:1
	v_add_f32_dpp v52, v52, v52 row_half_mirror row_mask:0xf bank_mask:0xf bound_ctrl:1
	ds_read_b128 v[98:101], v145 offset:3328
	v_add_f32_dpp v50, v50, v50 quad_perm:[2,3,0,1] row_mask:0xf bank_mask:0xf bound_ctrl:1
	v_add_f32_dpp v52, v52, v52 quad_perm:[2,3,0,1] row_mask:0xf bank_mask:0xf bound_ctrl:1
	ds_read_b128 v[102:105], v145 offset:3344
	v_add_f32_dpp v50, v50, v50 quad_perm:[1,0,3,2] row_mask:0xf bank_mask:0xf bound_ctrl:1
	v_add_f32_dpp v52, v52, v52 quad_perm:[1,0,3,2] row_mask:0xf bank_mask:0xf bound_ctrl:1
	v_pk_fma_f32 v[120:121], v[178:179], v[120:121], v[120:121] neg_lo:[1,0,0] neg_hi:[1,0,0]
	v_pk_fma_f32 v[122:123], v[180:181], v[122:123], v[122:123] neg_lo:[1,0,0] neg_hi:[1,0,0]
	v_pk_fma_f32 v[124:125], v[182:183], v[124:125], v[124:125] neg_lo:[1,0,0] neg_hi:[1,0,0]
	v_pk_fma_f32 v[126:127], v[184:185], v[126:127], v[126:127] neg_lo:[1,0,0] neg_hi:[1,0,0]
	v_cmp_eq_u32_e32 vcc, 1, v129
	v_pk_fma_f32 v[120:121], v[50:51], v[194:195], v[120:121] op_sel_hi:[0,1,1]
	v_fma_f32 v54, v50, v218, v52
	v_pk_fma_f32 v[122:123], v[50:51], v[196:197], v[122:123] op_sel_hi:[0,1,1]
	v_pk_fma_f32 v[124:125], v[50:51], v[198:199], v[124:125] op_sel_hi:[0,1,1]
	v_pk_fma_f32 v[126:127], v[50:51], v[200:201], v[126:127] op_sel_hi:[0,1,1]
	v_fma_f32 v55, v220, v219, v54
	v_pk_fma_f32 v[120:121], v[220:221], v[202:203], v[120:121] op_sel_hi:[0,1,1]
	v_pk_fma_f32 v[122:123], v[220:221], v[204:205], v[122:123] op_sel_hi:[0,1,1]
	v_cndmask_b32_e32 v49, v49, v55, vcc
	v_pk_fma_f32 v[124:125], v[220:221], v[206:207], v[124:125] op_sel_hi:[0,1,1]
	v_pk_fma_f32 v[126:127], v[220:221], v[208:209], v[126:127] op_sel_hi:[0,1,1]
	ds_read_b128 v[186:189], v145 offset:4096
	ds_read_b128 v[190:193], v145 offset:4112
	ds_read_b128 v[210:213], v145 offset:4864
	ds_read_b128 v[214:217], v145 offset:4880
	ds_read_b64 v[218:219], v56 offset:24
	ds_read_b32 v220, v146 offset:20672
	ds_read_b128 v[178:181], v145 offset:3840
	ds_read_b128 v[182:185], v145 offset:3856
	ds_read_b128 v[194:197], v145 offset:4352
	s_waitcnt lgkmcnt(9)
; #define LAS __attribute__((address_space(3)))
; __device__ __forceinline__ f32x2 fma2(f32x2 a, f32x2 b, f32x2 c) { return __builtin_elementwise_fma(a, b, c); }
; __device__ __forceinline__ float sum8(float x) { x += dppf<0x141>(x); x += dppf<0x4E>(x); x += dppf<0xB1>(x); return x; }
; __device__ __forceinline__ ROps8 r_ld8(const LAS float* B, int t, int kq, int vidx) {
;     ROps8 o; const LAS float* V = B + t * 320 + kq * 8;
; #pragma unroll
;     for (int h = 0; h < 2; ++h) { o.u[h] = *(const LAS f32x4*)(V + 4 * h); o.a[h] = *(const LAS f32x4*)(V + 64 + 4 * h); o.b[h] = *(const LAS f32x4*)(V + 128 + 4 * h); o.k[h] = *(const LAS f32x4*)(V + 192 + 4 * h); o.w[h] = *(const LAS f32x4*)(V + 256 + 4 * h); }
;     o.v = B[5120 + t * 16 + vidx]; o.sc = *(const LAS f32x2*)(B + 5376 + t * 2); return o;
; template <int TB> __device__ __forceinline__ void rwkv_block8(f32x2 (&S)[4], const LAS float* B, int kq, int vidx, float* yo) {
;     ...
;     for (int tt = 0; tt < SCAN_UNR; ++tt) {
;         const int t = t0 + tt;
;         const ROps8 n = r_ld8(B, (t + 1) & 15, kq, vidx);
;         const f32x2 a[4] = PAIRS(c.a), w[4] = PAIRS(c.w), u[4] = PAIRS(c.u), b[4] = PAIRS(c.b), k[4] = PAIRS(c.k);
;         const f32x2 ps = fma2(S[3], a[3], fma2(S[2], a[2], fma2(S[1], a[1], S[0] * a[0]))), py = fma2(S[3], w[3], fma2(S[2], w[2], fma2(S[1], w[1], S[0] * w[0])));
;         const float sa = sum8(ps.x + ps.y), yp = sum8(py.x + py.y);
;         const f32x2 sa2 = {sa, sa}, v2 = {c.v, c.v};
; #pragma unroll
;         for (int e = 0; e < 4; ++e) { S[e] = fma2(-u[e], S[e], S[e]); S[e] = fma2(sa2, b[e], S[e]); S[e] = fma2(v2, k[e], S[e]); }
;         const float y = yp + sa * c.sc.x + c.v * c.sc.y;
;         ykA = (kq == t) ? y : ykA; ykB = (kq + 8 == t) ? y : ykB;
;         c = n;
	v_pk_mul_f32 v[50:51], v[120:121], v[82:83]
	v_pk_mul_f32 v[52:53], v[120:121], v[106:107]
	v_pk_fma_f32 v[50:51], v[122:123], v[84:85], v[50:51]
	v_pk_fma_f32 v[52:53], v[122:123], v[108:109], v[52:53]
	v_pk_fma_f32 v[50:51], v[124:125], v[86:87], v[50:51]
	v_pk_fma_f32 v[52:53], v[124:125], v[110:111], v[52:53]
	v_pk_fma_f32 v[50:51], v[126:127], v[88:89], v[50:51]
	v_pk_fma_f32 v[52:53], v[126:127], v[112:113], v[52:53]
	v_add_f32_e32 v50, v50, v51
	v_add_f32_e32 v52, v52, v53
	ds_read_b128 v[198:201], v145 offset:4368
	v_add_f32_dpp v50, v50, v50 row_half_mirror row_mask:0xf bank_mask:0xf bound_ctrl:1
	v_add_f32_dpp v52, v52, v52 row_half_mirror row_mask:0xf bank_mask:0xf bound_ctrl:1
	ds_read_b128 v[202:205], v145 offset:4608
	v_add_f32_dpp v50, v50, v50 quad_perm:[2,3,0,1] row_mask:0xf bank_mask:0xf bound_ctrl:1
	v_add_f32_dpp v52, v52, v52 quad_perm:[2,3,0,1] row_mask:0xf bank_mask:0xf bound_ctrl:1
	ds_read_b128 v[206:209], v145 offset:4624
	v_add_f32_dpp v50, v50, v50 quad_perm:[1,0,3,2] row_mask:0xf bank_mask:0xf bound_ctrl:1
	v_add_f32_dpp v52, v52, v52 quad_perm:[1,0,3,2] row_mask:0xf bank_mask:0xf bound_ctrl:1
	v_pk_fma_f32 v[120:121], v[74:75], v[120:121], v[120:121] neg_lo:[1,0,0] neg_hi:[1,0,0]
	v_pk_fma_f32 v[122:123], v[76:77], v[122:123], v[122:123] neg_lo:[1,0,0] neg_hi:[1,0,0]
	v_pk_fma_f32 v[124:125], v[78:79], v[124:125], v[124:125] neg_lo:[1,0,0] neg_hi:[1,0,0]
	v_pk_fma_f32 v[126:127], v[80:81], v[126:127], v[126:127] neg_lo:[1,0,0] neg_hi:[1,0,0]
	v_cmp_eq_u32_e32 vcc, 2, v129
	v_pk_fma_f32 v[120:121], v[50:51], v[90:91], v[120:121] op_sel_hi:[0,1,1]
	v_fma_f32 v54, v50, v114, v52
	v_pk_fma_f32 v[122:123], v[50:51], v[92:93], v[122:123] op_sel_hi:[0,1,1]
	v_pk_fma_f32 v[124:125], v[50:51], v[94:95], v[124:125] op_sel_hi:[0,1,1]
	v_pk_fma_f32 v[126:127], v[50:51], v[96:97], v[126:127] op_sel_hi:[0,1,1]
	v_fma_f32 v55, v116, v115, v54
	v_pk_fma_f32 v[120:121], v[116:117], v[98:99], v[120:121] op_sel_hi:[0,1,1]
	v_pk_fma_f32 v[122:123], v[116:117], v[100:101], v[122:123] op_sel_hi:[0,1,1]
	v_cndmask_b32_e32 v49, v49, v55, vcc
	v_pk_fma_f32 v[124:125], v[116:117], v[102:103], v[124:125] op_sel_hi:[0,1,1]
	v_pk_fma_f32 v[126:127], v[116:117], v[104:105], v[126:127] op_sel_hi:[0,1,1]
	ds_read_b128 v[82:85], v145 offset:5376
	ds_read_b128 v[86:89], v145 offset:5392
	ds_read_b128 v[106:109], v145 offset:6144
	ds_read_b128 v[110:113], v145 offset:6160
	ds_read_b64 v[114:115], v56 offset:32
	ds_read_b32 v116, v146 offset:20736
	ds_read_b128 v[74:77], v145 offset:5120
	ds_read_b128 v[78:81], v145 offset:5136
	ds_read_b128 v[90:93], v145 offset:5632
	s_waitcnt lgkmcnt(9)
	v_pk_mul_f32 v[50:51], v[120:121], v[186:187]
	v_pk_mul_f32 v[52:53], v[120:121], v[210:211]
	v_pk_fma_f32 v[50:51], v[122:123], v[188:189], v[50:51]
	v_pk_fma_f32 v[52:53], v[122:123], v[212:213], v[52:53]
	v_pk_fma_f32 v[50:51], v[124:125], v[190:191], v[50:51]
	v_pk_fma_f32 v[52:53], v[124:125], v[214:215], v[52:53]
	v_pk_fma_f32 v[50:51], v[126:127], v[192:193], v[50:51]
	v_pk_fma_f32 v[52:53], v[126:127], v[216:217], v[52:53]
	v_add_f32_e32 v50, v50, v51
	v_add_f32_e32 v52, v52, v53
	ds_read_b128 v[94:97], v145 offset:5648
	v_add_f32_dpp v50, v50, v50 row_half_mirror row_mask:0xf bank_mask:0xf bound_ctrl:1
	v_add_f32_dpp v52, v52, v52 row_half_mirror row_mask:0xf bank_mask:0xf bound_ctrl:1
	ds_read_b128 v[98:101], v145 offset:5888
	v_add_f32_dpp v50, v50, v50 quad_perm:[2,3,0,1] row_mask:0xf bank_mask:0xf bound_ctrl:1
	v_add_f32_dpp v52, v52, v52 quad_perm:[2,3,0,1] row_mask:0xf bank_mask:0xf bound_ctrl:1
	ds_read_b128 v[102:105], v145 offset:5904
	v_add_f32_dpp v50, v50, v50 quad_perm:[1,0,3,2] row_mask:0xf bank_mask:0xf bound_ctrl:1
	v_add_f32_dpp v52, v52, v52 quad_perm:[1,0,3,2] row_mask:0xf bank_mask:0xf bound_ctrl:1
	v_pk_fma_f32 v[120:121], v[178:179], v[120:121], v[120:121] neg_lo:[1,0,0] neg_hi:[1,0,0]
	v_pk_fma_f32 v[122:123], v[180:181], v[122:123], v[122:123] neg_lo:[1,0,0] neg_hi:[1,0,0]
	v_pk_fma_f32 v[124:125], v[182:183], v[124:125], v[124:125] neg_lo:[1,0,0] neg_hi:[1,0,0]
	v_pk_fma_f32 v[126:127], v[184:185], v[126:127], v[126:127] neg_lo:[1,0,0] neg_hi:[1,0,0]
	v_cmp_eq_u32_e32 vcc, 3, v129
	v_pk_fma_f32 v[120:121], v[50:51], v[194:195], v[120:121] op_sel_hi:[0,1,1]
	v_fma_f32 v54, v50, v218, v52
	v_pk_fma_f32 v[122:123], v[50:51], v[196:197], v[122:123] op_sel_hi:[0,1,1]
	v_pk_fma_f32 v[124:125], v[50:51], v[198:199], v[124:125] op_sel_hi:[0,1,1]
	v_pk_fma_f32 v[126:127], v[50:51], v[200:201], v[126:127] op_sel_hi:[0,1,1]
	v_fma_f32 v55, v220, v219, v54
	v_pk_fma_f32 v[120:121], v[220:221], v[202:203], v[120:121] op_sel_hi:[0,1,1]
	v_pk_fma_f32 v[122:123], v[220:221], v[204:205], v[122:123] op_sel_hi:[0,1,1]
	v_cndmask_b32_e32 v49, v49, v55, vcc
	v_pk_fma_f32 v[124:125], v[220:221], v[206:207], v[124:125] op_sel_hi:[0,1,1]
	v_pk_fma_f32 v[126:127], v[220:221], v[208:209], v[126:127] op_sel_hi:[0,1,1]
	ds_read_b128 v[186:189], v145 offset:6656
	ds_read_b128 v[190:193], v145 offset:6672
	ds_read_b128 v[210:213], v145 offset:7424
	ds_read_b128 v[214:217], v145 offset:7440
	ds_read_b64 v[218:219], v56 offset:40
	ds_read_b32 v220, v146 offset:20800
	ds_read_b128 v[178:181], v145 offset:6400
	ds_read_b128 v[182:185], v145 offset:6416
	ds_read_b128 v[194:197], v145 offset:6912
	s_waitcnt lgkmcnt(9)
; #define LAS __attribute__((address_space(3)))
; __device__ __forceinline__ f32x2 fma2(f32x2 a, f32x2 b, f32x2 c) { return __builtin_elementwise_fma(a, b, c); }
; __device__ __forceinline__ float sum8(float x) { x += dppf<0x141>(x); x += dppf<0x4E>(x); x += dppf<0xB1>(x); return x; }
; __device__ __forceinline__ ROps8 r_ld8(const LAS float* B, int t, int kq, int vidx) {
;     ROps8 o; const LAS float* V = B + t * 320 + kq * 8;
; #pragma unroll
;     for (int h = 0; h < 2; ++h) { o.u[h] = *(const LAS f32x4*)(V + 4 * h); o.a[h] = *(const LAS f32x4*)(V + 64 + 4 * h); o.b[h] = *(const LAS f32x4*)(V + 128 + 4 * h); o.k[h] = *(const LAS f32x4*)(V + 192 + 4 * h); o.w[h] = *(const LAS f32x4*)(V + 256 + 4 * h); }
;     o.v = B[5120 + t * 16 + vidx]; o.sc = *(const LAS f32x2*)(B + 5376 + t * 2); return o;
; template <int TB> __device__ __forceinline__ void rwkv_block8(f32x2 (&S)[4], const LAS float* B, int kq, int vidx, float* yo) {
;     ...
;     for (int tt = 0; tt < SCAN_UNR; ++tt) {
;         const int t = t0 + tt;
;         const ROps8 n = r_ld8(B, (t + 1) & 15, kq, vidx);
;         const f32x2 a[4] = PAIRS(c.a), w[4] = PAIRS(c.w), u[4] = PAIRS(c.u), b[4] = PAIRS(c.b), k[4] = PAIRS(c.k);
;         const f32x2 ps = fma2(S[3], a[3], fma2(S[2], a[2], fma2(S[1], a[1], S[0] * a[0]))), py = fma2(S[3], w[3], fma2(S[2], w[2], fma2(S[1], w[1], S[0] * w[0])));
;         const float sa = sum8(ps.x + ps.y), yp = sum8(py.x + py.y);
;         const f32x2 sa2 = {sa, sa}, v2 = {c.v, c.v};
; #pragma unroll
;         for (int e = 0; e < 4; ++e) { S[e] = fma2(-u[e], S[e], S[e]); S[e] = fma2(sa2, b[e], S[e]); S[e] = fma2(v2, k[e], S[e]); }
;         const float y = yp + sa * c.sc.x + c.v * c.sc.y;
;         ykA = (kq == t) ? y : ykA; ykB = (kq + 8 == t) ? y : ykB;
;         c = n;
	v_pk_mul_f32 v[50:51], v[120:121], v[82:83]
	v_pk_mul_f32 v[52:53], v[120:121], v[106:107]
	v_pk_fma_f32 v[50:51], v[122:123], v[84:85], v[50:51]
	v_pk_fma_f32 v[52:53], v[122:123], v[108:109], v[52:53]
	v_pk_fma_f32 v[50:51], v[124:125], v[86:87], v[50:51]
	v_pk_fma_f32 v[52:53], v[124:125], v[110:111], v[52:53]
	v_pk_fma_f32 v[50:51], v[126:127], v[88:89], v[50:51]
	v_pk_fma_f32 v[52:53], v[126:127], v[112:113], v[52:53]
	v_add_f32_e32 v50, v50, v51
	v_add_f32_e32 v52, v52, v53
	ds_read_b128 v[198:201], v145 offset:6928
	v_add_f32_dpp v50, v50, v50 row_half_mirror row_mask:0xf bank_mask:0xf bound_ctrl:1
	v_add_f32_dpp v52, v52, v52 row_half_mirror row_mask:0xf bank_mask:0xf bound_ctrl:1
	ds_read_b128 v[202:205], v145 offset:7168
	v_add_f32_dpp v50, v50, v50 quad_perm:[2,3,0,1] row_mask:0xf bank_mask:0xf bound_ctrl:1
	v_add_f32_dpp v52, v52, v52 quad_perm:[2,3,0,1] row_mask:0xf bank_mask:0xf bound_ctrl:1
	ds_read_b128 v[206:209], v145 offset:7184
	v_add_f32_dpp v50, v50, v50 quad_perm:[1,0,3,2] row_mask:0xf bank_mask:0xf bound_ctrl:1
	v_add_f32_dpp v52, v52, v52 quad_perm:[1,0,3,2] row_mask:0xf bank_mask:0xf bound_ctrl:1
	v_pk_fma_f32 v[120:121], v[74:75], v[120:121], v[120:121] neg_lo:[1,0,0] neg_hi:[1,0,0]
	v_pk_fma_f32 v[122:123], v[76:77], v[122:123], v[122:123] neg_lo:[1,0,0] neg_hi:[1,0,0]
	v_pk_fma_f32 v[124:125], v[78:79], v[124:125], v[124:125] neg_lo:[1,0,0] neg_hi:[1,0,0]
	v_pk_fma_f32 v[126:127], v[80:81], v[126:127], v[126:127] neg_lo:[1,0,0] neg_hi:[1,0,0]
	v_cmp_eq_u32_e32 vcc, 4, v129
	v_pk_fma_f32 v[120:121], v[50:51], v[90:91], v[120:121] op_sel_hi:[0,1,1]
	v_fma_f32 v54, v50, v114, v52
	v_pk_fma_f32 v[122:123], v[50:51], v[92:93], v[122:123] op_sel_hi:[0,1,1]
	v_pk_fma_f32 v[124:125], v[50:51], v[94:95], v[124:125] op_sel_hi:[0,1,1]
	v_pk_fma_f32 v[126:127], v[50:51], v[96:97], v[126:127] op_sel_hi:[0,1,1]
	v_fma_f32 v55, v116, v115, v54
	v_pk_fma_f32 v[120:121], v[116:117], v[98:99], v[120:121] op_sel_hi:[0,1,1]
	v_pk_fma_f32 v[122:123], v[116:117], v[100:101], v[122:123] op_sel_hi:[0,1,1]
	v_cndmask_b32_e32 v49, v49, v55, vcc
	v_pk_fma_f32 v[124:125], v[116:117], v[102:103], v[124:125] op_sel_hi:[0,1,1]
	v_pk_fma_f32 v[126:127], v[116:117], v[104:105], v[126:127] op_sel_hi:[0,1,1]
	ds_read_b128 v[82:85], v145 offset:7936
	ds_read_b128 v[86:89], v145 offset:7952
	ds_read_b128 v[106:109], v145 offset:8704
	ds_read_b128 v[110:113], v145 offset:8720
	ds_read_b64 v[114:115], v56 offset:48
	ds_read_b32 v116, v146 offset:20864
	ds_read_b128 v[74:77], v145 offset:7680
	ds_read_b128 v[78:81], v145 offset:7696
	ds_read_b128 v[90:93], v145 offset:8192
	s_waitcnt lgkmcnt(9)
	v_pk_mul_f32 v[50:51], v[120:121], v[186:187]
	v_pk_mul_f32 v[52:53], v[120:121], v[210:211]
	v_pk_fma_f32 v[50:51], v[122:123], v[188:189], v[50:51]
	v_pk_fma_f32 v[52:53], v[122:123], v[212:213], v[52:53]
	v_pk_fma_f32 v[50:51], v[124:125], v[190:191], v[50:51]
	v_pk_fma_f32 v[52:53], v[124:125], v[214:215], v[52:53]
	v_pk_fma_f32 v[50:51], v[126:127], v[192:193], v[50:51]
	v_pk_fma_f32 v[52:53], v[126:127], v[216:217], v[52:53]
	v_add_f32_e32 v50, v50, v51
	v_add_f32_e32 v52, v52, v53
	ds_read_b128 v[94:97], v145 offset:8208
	v_add_f32_dpp v50, v50, v50 row_half_mirror row_mask:0xf bank_mask:0xf bound_ctrl:1
	v_add_f32_dpp v52, v52, v52 row_half_mirror row_mask:0xf bank_mask:0xf bound_ctrl:1
	ds_read_b128 v[98:101], v145 offset:8448
	v_add_f32_dpp v50, v50, v50 quad_perm:[2,3,0,1] row_mask:0xf bank_mask:0xf bound_ctrl:1
	v_add_f32_dpp v52, v52, v52 quad_perm:[2,3,0,1] row_mask:0xf bank_mask:0xf bound_ctrl:1
	ds_read_b128 v[102:105], v145 offset:8464
	v_add_f32_dpp v50, v50, v50 quad_perm:[1,0,3,2] row_mask:0xf bank_mask:0xf bound_ctrl:1
	v_add_f32_dpp v52, v52, v52 quad_perm:[1,0,3,2] row_mask:0xf bank_mask:0xf bound_ctrl:1
	v_pk_fma_f32 v[120:121], v[178:179], v[120:121], v[120:121] neg_lo:[1,0,0] neg_hi:[1,0,0]
	v_pk_fma_f32 v[122:123], v[180:181], v[122:123], v[122:123] neg_lo:[1,0,0] neg_hi:[1,0,0]
	v_pk_fma_f32 v[124:125], v[182:183], v[124:125], v[124:125] neg_lo:[1,0,0] neg_hi:[1,0,0]
	v_pk_fma_f32 v[126:127], v[184:185], v[126:127], v[126:127] neg_lo:[1,0,0] neg_hi:[1,0,0]
	v_cmp_eq_u32_e32 vcc, 5, v129
	v_pk_fma_f32 v[120:121], v[50:51], v[194:195], v[120:121] op_sel_hi:[0,1,1]
	v_fma_f32 v54, v50, v218, v52
	v_pk_fma_f32 v[122:123], v[50:51], v[196:197], v[122:123] op_sel_hi:[0,1,1]
	v_pk_fma_f32 v[124:125], v[50:51], v[198:199], v[124:125] op_sel_hi:[0,1,1]
	v_pk_fma_f32 v[126:127], v[50:51], v[200:201], v[126:127] op_sel_hi:[0,1,1]
	v_fma_f32 v55, v220, v219, v54
	v_pk_fma_f32 v[120:121], v[220:221], v[202:203], v[120:121] op_sel_hi:[0,1,1]
	v_pk_fma_f32 v[122:123], v[220:221], v[204:205], v[122:123] op_sel_hi:[0,1,1]
	v_cndmask_b32_e32 v49, v49, v55, vcc
	v_pk_fma_f32 v[124:125], v[220:221], v[206:207], v[124:125] op_sel_hi:[0,1,1]
	v_pk_fma_f32 v[126:127], v[220:221], v[208:209], v[126:127] op_sel_hi:[0,1,1]
	ds_read_b128 v[186:189], v145 offset:9216
	ds_read_b128 v[190:193], v145 offset:9232
	ds_read_b128 v[210:213], v145 offset:9984
	ds_read_b128 v[214:217], v145 offset:10000
	ds_read_b64 v[218:219], v56 offset:56
	ds_read_b32 v220, v146 offset:20928
	ds_read_b128 v[178:181], v145 offset:8960
	ds_read_b128 v[182:185], v145 offset:8976
	ds_read_b128 v[194:197], v145 offset:9472
	s_waitcnt lgkmcnt(9)
; #define LAS __attribute__((address_space(3)))
; __device__ __forceinline__ f32x2 fma2(f32x2 a, f32x2 b, f32x2 c) { return __builtin_elementwise_fma(a, b, c); }
; __device__ __forceinline__ float sum8(float x) { x += dppf<0x141>(x); x += dppf<0x4E>(x); x += dppf<0xB1>(x); return x; }
; __device__ __forceinline__ ROps8 r_ld8(const LAS float* B, int t, int kq, int vidx) {
;     ROps8 o; const LAS float* V = B + t * 320 + kq * 8;
; #pragma unroll
;     for (int h = 0; h < 2; ++h) { o.u[h] = *(const LAS f32x4*)(V + 4 * h); o.a[h] = *(const LAS f32x4*)(V + 64 + 4 * h); o.b[h] = *(const LAS f32x4*)(V + 128 + 4 * h); o.k[h] = *(const LAS f32x4*)(V + 192 + 4 * h); o.w[h] = *(const LAS f32x4*)(V + 256 + 4 * h); }
;     o.v = B[5120 + t * 16 + vidx]; o.sc = *(const LAS f32x2*)(B + 5376 + t * 2); return o;
; template <int TB> __device__ __forceinline__ void rwkv_block8(f32x2 (&S)[4], const LAS float* B, int kq, int vidx, float* yo) {
;     ...
;     for (int tt = 0; tt < SCAN_UNR; ++tt) {
;         const int t = t0 + tt;
;         const ROps8 n = r_ld8(B, (t + 1) & 15, kq, vidx);
;         const f32x2 a[4] = PAIRS(c.a), w[4] = PAIRS(c.w), u[4] = PAIRS(c.u), b[4] = PAIRS(c.b), k[4] = PAIRS(c.k);
;         const f32x2 ps = fma2(S[3], a[3], fma2(S[2], a[2], fma2(S[1], a[1], S[0] * a[0]))), py = fma2(S[3], w[3], fma2(S[2], w[2], fma2(S[1], w[1], S[0] * w[0])));
;         const float sa = sum8(ps.x + ps.y), yp = sum8(py.x + py.y);
;         const f32x2 sa2 = {sa, sa}, v2 = {c.v, c.v};
; #pragma unroll
;         for (int e = 0; e < 4; ++e) { S[e] = fma2(-u[e], S[e], S[e]); S[e] = fma2(sa2, b[e], S[e]); S[e] = fma2(v2, k[e], S[e]); }
;         const float y = yp + sa * c.sc.x + c.v * c.sc.y;
;         ykA = (kq == t) ? y : ykA; ykB = (kq + 8 == t) ? y : ykB;
;         c = n;
	v_pk_mul_f32 v[50:51], v[120:121], v[82:83]
	v_pk_mul_f32 v[52:53], v[120:121], v[106:107]
	v_pk_fma_f32 v[50:51], v[122:123], v[84:85], v[50:51]
	v_pk_fma_f32 v[52:53], v[122:123], v[108:109], v[52:53]
	v_pk_fma_f32 v[50:51], v[124:125], v[86:87], v[50:51]
	v_pk_fma_f32 v[52:53], v[124:125], v[110:111], v[52:53]
	v_pk_fma_f32 v[50:51], v[126:127], v[88:89], v[50:51]
	v_pk_fma_f32 v[52:53], v[126:127], v[112:113], v[52:53]
	v_add_f32_e32 v50, v50, v51
	v_add_f32_e32 v52, v52, v53
	ds_read_b128 v[198:201], v145 offset:9488
	v_add_f32_dpp v50, v50, v50 row_half_mirror row_mask:0xf bank_mask:0xf bound_ctrl:1
	v_add_f32_dpp v52, v52, v52 row_half_mirror row_mask:0xf bank_mask:0xf bound_ctrl:1
	ds_read_b128 v[202:205], v145 offset:9728
	v_add_f32_dpp v50, v50, v50 quad_perm:[2,3,0,1] row_mask:0xf bank_mask:0xf bound_ctrl:1
	v_add_f32_dpp v52, v52, v52 quad_perm:[2,3,0,1] row_mask:0xf bank_mask:0xf bound_ctrl:1
	ds_read_b128 v[206:209], v145 offset:9744
	v_add_f32_dpp v50, v50, v50 quad_perm:[1,0,3,2] row_mask:0xf bank_mask:0xf bound_ctrl:1
	v_add_f32_dpp v52, v52, v52 quad_perm:[1,0,3,2] row_mask:0xf bank_mask:0xf bound_ctrl:1
	v_pk_fma_f32 v[120:121], v[74:75], v[120:121], v[120:121] neg_lo:[1,0,0] neg_hi:[1,0,0]
	v_pk_fma_f32 v[122:123], v[76:77], v[122:123], v[122:123] neg_lo:[1,0,0] neg_hi:[1,0,0]
	v_pk_fma_f32 v[124:125], v[78:79], v[124:125], v[124:125] neg_lo:[1,0,0] neg_hi:[1,0,0]
	v_pk_fma_f32 v[126:127], v[80:81], v[126:127], v[126:127] neg_lo:[1,0,0] neg_hi:[1,0,0]
	v_cmp_eq_u32_e32 vcc, 6, v129
	v_pk_fma_f32 v[120:121], v[50:51], v[90:91], v[120:121] op_sel_hi:[0,1,1]
	v_fma_f32 v54, v50, v114, v52
	v_pk_fma_f32 v[122:123], v[50:51], v[92:93], v[122:123] op_sel_hi:[0,1,1]
	v_pk_fma_f32 v[124:125], v[50:51], v[94:95], v[124:125] op_sel_hi:[0,1,1]
	v_pk_fma_f32 v[126:127], v[50:51], v[96:97], v[126:127] op_sel_hi:[0,1,1]
	v_fma_f32 v55, v116, v115, v54
	v_pk_fma_f32 v[120:121], v[116:117], v[98:99], v[120:121] op_sel_hi:[0,1,1]
	v_pk_fma_f32 v[122:123], v[116:117], v[100:101], v[122:123] op_sel_hi:[0,1,1]
	v_cndmask_b32_e32 v49, v49, v55, vcc
	v_pk_fma_f32 v[124:125], v[116:117], v[102:103], v[124:125] op_sel_hi:[0,1,1]
	v_pk_fma_f32 v[126:127], v[116:117], v[104:105], v[126:127] op_sel_hi:[0,1,1]
	ds_read_b128 v[82:85], v145 offset:10496
	ds_read_b128 v[86:89], v145 offset:10512
	ds_read_b128 v[106:109], v145 offset:11264
	ds_read_b128 v[110:113], v145 offset:11280
	ds_read_b64 v[114:115], v56 offset:64
	ds_read_b32 v116, v146 offset:20992
	ds_read_b128 v[74:77], v145 offset:10240
	ds_read_b128 v[78:81], v145 offset:10256
	ds_read_b128 v[90:93], v145 offset:10752
	s_waitcnt lgkmcnt(9)
	v_pk_mul_f32 v[50:51], v[120:121], v[186:187]
	v_pk_mul_f32 v[52:53], v[120:121], v[210:211]
	v_pk_fma_f32 v[50:51], v[122:123], v[188:189], v[50:51]
	v_pk_fma_f32 v[52:53], v[122:123], v[212:213], v[52:53]
	v_pk_fma_f32 v[50:51], v[124:125], v[190:191], v[50:51]
	v_pk_fma_f32 v[52:53], v[124:125], v[214:215], v[52:53]
	v_pk_fma_f32 v[50:51], v[126:127], v[192:193], v[50:51]
	v_pk_fma_f32 v[52:53], v[126:127], v[216:217], v[52:53]
	v_add_f32_e32 v50, v50, v51
	v_add_f32_e32 v52, v52, v53
	ds_read_b128 v[94:97], v145 offset:10768
	v_add_f32_dpp v50, v50, v50 row_half_mirror row_mask:0xf bank_mask:0xf bound_ctrl:1
	v_add_f32_dpp v52, v52, v52 row_half_mirror row_mask:0xf bank_mask:0xf bound_ctrl:1
	ds_read_b128 v[98:101], v145 offset:11008
	v_add_f32_dpp v50, v50, v50 quad_perm:[2,3,0,1] row_mask:0xf bank_mask:0xf bound_ctrl:1
	v_add_f32_dpp v52, v52, v52 quad_perm:[2,3,0,1] row_mask:0xf bank_mask:0xf bound_ctrl:1
	ds_read_b128 v[102:105], v145 offset:11024
	v_add_f32_dpp v50, v50, v50 quad_perm:[1,0,3,2] row_mask:0xf bank_mask:0xf bound_ctrl:1
	v_add_f32_dpp v52, v52, v52 quad_perm:[1,0,3,2] row_mask:0xf bank_mask:0xf bound_ctrl:1
	v_pk_fma_f32 v[120:121], v[178:179], v[120:121], v[120:121] neg_lo:[1,0,0] neg_hi:[1,0,0]
	v_pk_fma_f32 v[122:123], v[180:181], v[122:123], v[122:123] neg_lo:[1,0,0] neg_hi:[1,0,0]
	v_pk_fma_f32 v[124:125], v[182:183], v[124:125], v[124:125] neg_lo:[1,0,0] neg_hi:[1,0,0]
	v_pk_fma_f32 v[126:127], v[184:185], v[126:127], v[126:127] neg_lo:[1,0,0] neg_hi:[1,0,0]
	v_cmp_eq_u32_e32 vcc, 7, v129
	v_pk_fma_f32 v[120:121], v[50:51], v[194:195], v[120:121] op_sel_hi:[0,1,1]
	v_fma_f32 v54, v50, v218, v52
	v_pk_fma_f32 v[122:123], v[50:51], v[196:197], v[122:123] op_sel_hi:[0,1,1]
	v_pk_fma_f32 v[124:125], v[50:51], v[198:199], v[124:125] op_sel_hi:[0,1,1]
	v_pk_fma_f32 v[126:127], v[50:51], v[200:201], v[126:127] op_sel_hi:[0,1,1]
	v_fma_f32 v55, v220, v219, v54
	v_pk_fma_f32 v[120:121], v[220:221], v[202:203], v[120:121] op_sel_hi:[0,1,1]
	v_pk_fma_f32 v[122:123], v[220:221], v[204:205], v[122:123] op_sel_hi:[0,1,1]
	v_cndmask_b32_e32 v49, v49, v55, vcc
	v_pk_fma_f32 v[124:125], v[220:221], v[206:207], v[124:125] op_sel_hi:[0,1,1]
	v_pk_fma_f32 v[126:127], v[220:221], v[208:209], v[126:127] op_sel_hi:[0,1,1]
	ds_read_b128 v[186:189], v145 offset:11776
	ds_read_b128 v[190:193], v145 offset:11792
	ds_read_b128 v[210:213], v145 offset:12544
	ds_read_b128 v[214:217], v145 offset:12560
	ds_read_b64 v[218:219], v56 offset:72
	ds_read_b32 v220, v146 offset:21056
	ds_read_b128 v[178:181], v145 offset:11520
	ds_read_b128 v[182:185], v145 offset:11536
	ds_read_b128 v[194:197], v145 offset:12032
	s_waitcnt lgkmcnt(9)
; #define LAS __attribute__((address_space(3)))
; __device__ __forceinline__ f32x2 fma2(f32x2 a, f32x2 b, f32x2 c) { return __builtin_elementwise_fma(a, b, c); }
; __device__ __forceinline__ float sum8(float x) { x += dppf<0x141>(x); x += dppf<0x4E>(x); x += dppf<0xB1>(x); return x; }
; __device__ __forceinline__ ROps8 r_ld8(const LAS float* B, int t, int kq, int vidx) {
;     ROps8 o; const LAS float* V = B + t * 320 + kq * 8;
; #pragma unroll
;     for (int h = 0; h < 2; ++h) { o.u[h] = *(const LAS f32x4*)(V + 4 * h); o.a[h] = *(const LAS f32x4*)(V + 64 + 4 * h); o.b[h] = *(const LAS f32x4*)(V + 128 + 4 * h); o.k[h] = *(const LAS f32x4*)(V + 192 + 4 * h); o.w[h] = *(const LAS f32x4*)(V + 256 + 4 * h); }
;     o.v = B[5120 + t * 16 + vidx]; o.sc = *(const LAS f32x2*)(B + 5376 + t * 2); return o;
; template <int TB> __device__ __forceinline__ void rwkv_block8(f32x2 (&S)[4], const LAS float* B, int kq, int vidx, float* yo) {
;     ...
;     for (int tt = 0; tt < SCAN_UNR; ++tt) {
;         const int t = t0 + tt;
;         const ROps8 n = r_ld8(B, (t + 1) & 15, kq, vidx);
;         const f32x2 a[4] = PAIRS(c.a), w[4] = PAIRS(c.w), u[4] = PAIRS(c.u), b[4] = PAIRS(c.b), k[4] = PAIRS(c.k);
;         const f32x2 ps = fma2(S[3], a[3], fma2(S[2], a[2], fma2(S[1], a[1], S[0] * a[0]))), py = fma2(S[3], w[3], fma2(S[2], w[2], fma2(S[1], w[1], S[0] * w[0])));
;         const float sa = sum8(ps.x + ps.y), yp = sum8(py.x + py.y);
;         const f32x2 sa2 = {sa, sa}, v2 = {c.v, c.v};
; #pragma unroll
;         for (int e = 0; e < 4; ++e) { S[e] = fma2(-u[e], S[e], S[e]); S[e] = fma2(sa2, b[e], S[e]); S[e] = fma2(v2, k[e], S[e]); }
;         const float y = yp + sa * c.sc.x + c.v * c.sc.y;
;         ykA = (kq == t) ? y : ykA; ykB = (kq + 8 == t) ? y : ykB;
;         c = n;
	v_pk_mul_f32 v[50:51], v[120:121], v[82:83]
	v_pk_mul_f32 v[52:53], v[120:121], v[106:107]
	v_pk_fma_f32 v[50:51], v[122:123], v[84:85], v[50:51]
	v_pk_fma_f32 v[52:53], v[122:123], v[108:109], v[52:53]
	v_pk_fma_f32 v[50:51], v[124:125], v[86:87], v[50:51]
	v_pk_fma_f32 v[52:53], v[124:125], v[110:111], v[52:53]
	v_pk_fma_f32 v[50:51], v[126:127], v[88:89], v[50:51]
	v_pk_fma_f32 v[52:53], v[126:127], v[112:113], v[52:53]
	v_add_f32_e32 v50, v50, v51
	v_add_f32_e32 v52, v52, v53
	ds_read_b128 v[198:201], v145 offset:12048
	v_add_f32_dpp v50, v50, v50 row_half_mirror row_mask:0xf bank_mask:0xf bound_ctrl:1
	v_add_f32_dpp v52, v52, v52 row_half_mirror row_mask:0xf bank_mask:0xf bound_ctrl:1
	ds_read_b128 v[202:205], v145 offset:12288
	v_add_f32_dpp v50, v50, v50 quad_perm:[2,3,0,1] row_mask:0xf bank_mask:0xf bound_ctrl:1
	v_add_f32_dpp v52, v52, v52 quad_perm:[2,3,0,1] row_mask:0xf bank_mask:0xf bound_ctrl:1
	ds_read_b128 v[206:209], v145 offset:12304
	v_add_f32_dpp v50, v50, v50 quad_perm:[1,0,3,2] row_mask:0xf bank_mask:0xf bound_ctrl:1
	v_add_f32_dpp v52, v52, v52 quad_perm:[1,0,3,2] row_mask:0xf bank_mask:0xf bound_ctrl:1
	v_pk_fma_f32 v[120:121], v[74:75], v[120:121], v[120:121] neg_lo:[1,0,0] neg_hi:[1,0,0]
	v_pk_fma_f32 v[122:123], v[76:77], v[122:123], v[122:123] neg_lo:[1,0,0] neg_hi:[1,0,0]
	v_pk_fma_f32 v[124:125], v[78:79], v[124:125], v[124:125] neg_lo:[1,0,0] neg_hi:[1,0,0]
	v_pk_fma_f32 v[126:127], v[80:81], v[126:127], v[126:127] neg_lo:[1,0,0] neg_hi:[1,0,0]
	v_cmp_eq_u32_e32 vcc, 0, v129
	v_pk_fma_f32 v[120:121], v[50:51], v[90:91], v[120:121] op_sel_hi:[0,1,1]
	v_fma_f32 v54, v50, v114, v52
	v_pk_fma_f32 v[122:123], v[50:51], v[92:93], v[122:123] op_sel_hi:[0,1,1]
	v_pk_fma_f32 v[124:125], v[50:51], v[94:95], v[124:125] op_sel_hi:[0,1,1]
	v_pk_fma_f32 v[126:127], v[50:51], v[96:97], v[126:127] op_sel_hi:[0,1,1]
	v_fma_f32 v55, v116, v115, v54
	v_pk_fma_f32 v[120:121], v[116:117], v[98:99], v[120:121] op_sel_hi:[0,1,1]
	v_pk_fma_f32 v[122:123], v[116:117], v[100:101], v[122:123] op_sel_hi:[0,1,1]
	v_cndmask_b32_e32 v48, v48, v55, vcc
	v_pk_fma_f32 v[124:125], v[116:117], v[102:103], v[124:125] op_sel_hi:[0,1,1]
	v_pk_fma_f32 v[126:127], v[116:117], v[104:105], v[126:127] op_sel_hi:[0,1,1]
	ds_read_b128 v[82:85], v145 offset:13056
	ds_read_b128 v[86:89], v145 offset:13072
	ds_read_b128 v[106:109], v145 offset:13824
	ds_read_b128 v[110:113], v145 offset:13840
	ds_read_b64 v[114:115], v56 offset:80
	ds_read_b32 v116, v146 offset:21120
	ds_read_b128 v[74:77], v145 offset:12800
	ds_read_b128 v[78:81], v145 offset:12816
	ds_read_b128 v[90:93], v145 offset:13312
	s_waitcnt lgkmcnt(9)
	v_pk_mul_f32 v[50:51], v[120:121], v[186:187]
	v_pk_mul_f32 v[52:53], v[120:121], v[210:211]
	v_pk_fma_f32 v[50:51], v[122:123], v[188:189], v[50:51]
	v_pk_fma_f32 v[52:53], v[122:123], v[212:213], v[52:53]
	v_pk_fma_f32 v[50:51], v[124:125], v[190:191], v[50:51]
	v_pk_fma_f32 v[52:53], v[124:125], v[214:215], v[52:53]
	v_pk_fma_f32 v[50:51], v[126:127], v[192:193], v[50:51]
	v_pk_fma_f32 v[52:53], v[126:127], v[216:217], v[52:53]
	v_add_f32_e32 v50, v50, v51
	v_add_f32_e32 v52, v52, v53
	ds_read_b128 v[94:97], v145 offset:13328
	v_add_f32_dpp v50, v50, v50 row_half_mirror row_mask:0xf bank_mask:0xf bound_ctrl:1
	v_add_f32_dpp v52, v52, v52 row_half_mirror row_mask:0xf bank_mask:0xf bound_ctrl:1
	ds_read_b128 v[98:101], v145 offset:13568
	v_add_f32_dpp v50, v50, v50 quad_perm:[2,3,0,1] row_mask:0xf bank_mask:0xf bound_ctrl:1
	v_add_f32_dpp v52, v52, v52 quad_perm:[2,3,0,1] row_mask:0xf bank_mask:0xf bound_ctrl:1
	ds_read_b128 v[102:105], v145 offset:13584
	v_add_f32_dpp v50, v50, v50 quad_perm:[1,0,3,2] row_mask:0xf bank_mask:0xf bound_ctrl:1
	v_add_f32_dpp v52, v52, v52 quad_perm:[1,0,3,2] row_mask:0xf bank_mask:0xf bound_ctrl:1
	v_pk_fma_f32 v[120:121], v[178:179], v[120:121], v[120:121] neg_lo:[1,0,0] neg_hi:[1,0,0]
	v_pk_fma_f32 v[122:123], v[180:181], v[122:123], v[122:123] neg_lo:[1,0,0] neg_hi:[1,0,0]
	v_pk_fma_f32 v[124:125], v[182:183], v[124:125], v[124:125] neg_lo:[1,0,0] neg_hi:[1,0,0]
	v_pk_fma_f32 v[126:127], v[184:185], v[126:127], v[126:127] neg_lo:[1,0,0] neg_hi:[1,0,0]
	v_cmp_eq_u32_e32 vcc, 1, v129
	v_pk_fma_f32 v[120:121], v[50:51], v[194:195], v[120:121] op_sel_hi:[0,1,1]
	v_fma_f32 v54, v50, v218, v52
	v_pk_fma_f32 v[122:123], v[50:51], v[196:197], v[122:123] op_sel_hi:[0,1,1]
	v_pk_fma_f32 v[124:125], v[50:51], v[198:199], v[124:125] op_sel_hi:[0,1,1]
	v_pk_fma_f32 v[126:127], v[50:51], v[200:201], v[126:127] op_sel_hi:[0,1,1]
	v_fma_f32 v55, v220, v219, v54
	v_pk_fma_f32 v[120:121], v[220:221], v[202:203], v[120:121] op_sel_hi:[0,1,1]
	v_pk_fma_f32 v[122:123], v[220:221], v[204:205], v[122:123] op_sel_hi:[0,1,1]
	v_cndmask_b32_e32 v48, v48, v55, vcc
	v_pk_fma_f32 v[124:125], v[220:221], v[206:207], v[124:125] op_sel_hi:[0,1,1]
	v_pk_fma_f32 v[126:127], v[220:221], v[208:209], v[126:127] op_sel_hi:[0,1,1]
	ds_read_b128 v[186:189], v145 offset:14336
	ds_read_b128 v[190:193], v145 offset:14352
	ds_read_b128 v[210:213], v145 offset:15104
	ds_read_b128 v[214:217], v145 offset:15120
	ds_read_b64 v[218:219], v56 offset:88
	ds_read_b32 v220, v146 offset:21184
	ds_read_b128 v[178:181], v145 offset:14080
	ds_read_b128 v[182:185], v145 offset:14096
	ds_read_b128 v[194:197], v145 offset:14592
	s_waitcnt lgkmcnt(9)
; #define LAS __attribute__((address_space(3)))
; __device__ __forceinline__ f32x2 fma2(f32x2 a, f32x2 b, f32x2 c) { return __builtin_elementwise_fma(a, b, c); }
; __device__ __forceinline__ float sum8(float x) { x += dppf<0x141>(x); x += dppf<0x4E>(x); x += dppf<0xB1>(x); return x; }
; __device__ __forceinline__ ROps8 r_ld8(const LAS float* B, int t, int kq, int vidx) {
;     ROps8 o; const LAS float* V = B + t * 320 + kq * 8;
; #pragma unroll
;     for (int h = 0; h < 2; ++h) { o.u[h] = *(const LAS f32x4*)(V + 4 * h); o.a[h] = *(const LAS f32x4*)(V + 64 + 4 * h); o.b[h] = *(const LAS f32x4*)(V + 128 + 4 * h); o.k[h] = *(const LAS f32x4*)(V + 192 + 4 * h); o.w[h] = *(const LAS f32x4*)(V + 256 + 4 * h); }
;     o.v = B[5120 + t * 16 + vidx]; o.sc = *(const LAS f32x2*)(B + 5376 + t * 2); return o;
; template <int TB> __device__ __forceinline__ void rwkv_block8(f32x2 (&S)[4], const LAS float* B, int kq, int vidx, float* yo) {
;     ...
;     for (int tt = 0; tt < SCAN_UNR; ++tt) {
;         const int t = t0 + tt;
;         const ROps8 n = r_ld8(B, (t + 1) & 15, kq, vidx);
;         const f32x2 a[4] = PAIRS(c.a), w[4] = PAIRS(c.w), u[4] = PAIRS(c.u), b[4] = PAIRS(c.b), k[4] = PAIRS(c.k);
;         const f32x2 ps = fma2(S[3], a[3], fma2(S[2], a[2], fma2(S[1], a[1], S[0] * a[0]))), py = fma2(S[3], w[3], fma2(S[2], w[2], fma2(S[1], w[1], S[0] * w[0])));
;         const float sa = sum8(ps.x + ps.y), yp = sum8(py.x + py.y);
;         const f32x2 sa2 = {sa, sa}, v2 = {c.v, c.v};
; #pragma unroll
;         for (int e = 0; e < 4; ++e) { S[e] = fma2(-u[e], S[e], S[e]); S[e] = fma2(sa2, b[e], S[e]); S[e] = fma2(v2, k[e], S[e]); }
;         const float y = yp + sa * c.sc.x + c.v * c.sc.y;
;         ykA = (kq == t) ? y : ykA; ykB = (kq + 8 == t) ? y : ykB;
;         c = n;
	v_pk_mul_f32 v[50:51], v[120:121], v[82:83]
	v_pk_mul_f32 v[52:53], v[120:121], v[106:107]
	v_pk_fma_f32 v[50:51], v[122:123], v[84:85], v[50:51]
	v_pk_fma_f32 v[52:53], v[122:123], v[108:109], v[52:53]
	v_pk_fma_f32 v[50:51], v[124:125], v[86:87], v[50:51]
	v_pk_fma_f32 v[52:53], v[124:125], v[110:111], v[52:53]
	v_pk_fma_f32 v[50:51], v[126:127], v[88:89], v[50:51]
	v_pk_fma_f32 v[52:53], v[126:127], v[112:113], v[52:53]
	v_add_f32_e32 v50, v50, v51
	v_add_f32_e32 v52, v52, v53
	ds_read_b128 v[198:201], v145 offset:14608
	v_add_f32_dpp v50, v50, v50 row_half_mirror row_mask:0xf bank_mask:0xf bound_ctrl:1
	v_add_f32_dpp v52, v52, v52 row_half_mirror row_mask:0xf bank_mask:0xf bound_ctrl:1
	ds_read_b128 v[202:205], v145 offset:14848
	v_add_f32_dpp v50, v50, v50 quad_perm:[2,3,0,1] row_mask:0xf bank_mask:0xf bound_ctrl:1
	v_add_f32_dpp v52, v52, v52 quad_perm:[2,3,0,1] row_mask:0xf bank_mask:0xf bound_ctrl:1
	ds_read_b128 v[206:209], v145 offset:14864
	v_add_f32_dpp v50, v50, v50 quad_perm:[1,0,3,2] row_mask:0xf bank_mask:0xf bound_ctrl:1
	v_add_f32_dpp v52, v52, v52 quad_perm:[1,0,3,2] row_mask:0xf bank_mask:0xf bound_ctrl:1
	v_pk_fma_f32 v[120:121], v[74:75], v[120:121], v[120:121] neg_lo:[1,0,0] neg_hi:[1,0,0]
	v_pk_fma_f32 v[122:123], v[76:77], v[122:123], v[122:123] neg_lo:[1,0,0] neg_hi:[1,0,0]
	v_pk_fma_f32 v[124:125], v[78:79], v[124:125], v[124:125] neg_lo:[1,0,0] neg_hi:[1,0,0]
	v_pk_fma_f32 v[126:127], v[80:81], v[126:127], v[126:127] neg_lo:[1,0,0] neg_hi:[1,0,0]
	v_cmp_eq_u32_e32 vcc, 2, v129
	v_pk_fma_f32 v[120:121], v[50:51], v[90:91], v[120:121] op_sel_hi:[0,1,1]
	v_fma_f32 v54, v50, v114, v52
	v_pk_fma_f32 v[122:123], v[50:51], v[92:93], v[122:123] op_sel_hi:[0,1,1]
	v_pk_fma_f32 v[124:125], v[50:51], v[94:95], v[124:125] op_sel_hi:[0,1,1]
	v_pk_fma_f32 v[126:127], v[50:51], v[96:97], v[126:127] op_sel_hi:[0,1,1]
	v_fma_f32 v55, v116, v115, v54
	v_pk_fma_f32 v[120:121], v[116:117], v[98:99], v[120:121] op_sel_hi:[0,1,1]
	v_pk_fma_f32 v[122:123], v[116:117], v[100:101], v[122:123] op_sel_hi:[0,1,1]
	v_cndmask_b32_e32 v48, v48, v55, vcc
	v_pk_fma_f32 v[124:125], v[116:117], v[102:103], v[124:125] op_sel_hi:[0,1,1]
	v_pk_fma_f32 v[126:127], v[116:117], v[104:105], v[126:127] op_sel_hi:[0,1,1]
	ds_read_b128 v[82:85], v145 offset:15616
	ds_read_b128 v[86:89], v145 offset:15632
	ds_read_b128 v[106:109], v145 offset:16384
	ds_read_b128 v[110:113], v145 offset:16400
	ds_read_b64 v[114:115], v56 offset:96
	ds_read_b32 v116, v146 offset:21248
	ds_read_b128 v[74:77], v145 offset:15360
	ds_read_b128 v[78:81], v145 offset:15376
	ds_read_b128 v[90:93], v145 offset:15872
	s_waitcnt lgkmcnt(9)
	v_pk_mul_f32 v[50:51], v[120:121], v[186:187]
	v_pk_mul_f32 v[52:53], v[120:121], v[210:211]
	v_pk_fma_f32 v[50:51], v[122:123], v[188:189], v[50:51]
	v_pk_fma_f32 v[52:53], v[122:123], v[212:213], v[52:53]
	v_pk_fma_f32 v[50:51], v[124:125], v[190:191], v[50:51]
	v_pk_fma_f32 v[52:53], v[124:125], v[214:215], v[52:53]
	v_pk_fma_f32 v[50:51], v[126:127], v[192:193], v[50:51]
	v_pk_fma_f32 v[52:53], v[126:127], v[216:217], v[52:53]
	v_add_f32_e32 v50, v50, v51
	v_add_f32_e32 v52, v52, v53
	ds_read_b128 v[94:97], v145 offset:15888
	v_add_f32_dpp v50, v50, v50 row_half_mirror row_mask:0xf bank_mask:0xf bound_ctrl:1
	v_add_f32_dpp v52, v52, v52 row_half_mirror row_mask:0xf bank_mask:0xf bound_ctrl:1
	ds_read_b128 v[98:101], v145 offset:16128
	v_add_f32_dpp v50, v50, v50 quad_perm:[2,3,0,1] row_mask:0xf bank_mask:0xf bound_ctrl:1
	v_add_f32_dpp v52, v52, v52 quad_perm:[2,3,0,1] row_mask:0xf bank_mask:0xf bound_ctrl:1
	ds_read_b128 v[102:105], v145 offset:16144
	v_add_f32_dpp v50, v50, v50 quad_perm:[1,0,3,2] row_mask:0xf bank_mask:0xf bound_ctrl:1
	v_add_f32_dpp v52, v52, v52 quad_perm:[1,0,3,2] row_mask:0xf bank_mask:0xf bound_ctrl:1
	v_pk_fma_f32 v[120:121], v[178:179], v[120:121], v[120:121] neg_lo:[1,0,0] neg_hi:[1,0,0]
	v_pk_fma_f32 v[122:123], v[180:181], v[122:123], v[122:123] neg_lo:[1,0,0] neg_hi:[1,0,0]
	v_pk_fma_f32 v[124:125], v[182:183], v[124:125], v[124:125] neg_lo:[1,0,0] neg_hi:[1,0,0]
	v_pk_fma_f32 v[126:127], v[184:185], v[126:127], v[126:127] neg_lo:[1,0,0] neg_hi:[1,0,0]
	v_cmp_eq_u32_e32 vcc, 3, v129
	v_pk_fma_f32 v[120:121], v[50:51], v[194:195], v[120:121] op_sel_hi:[0,1,1]
	v_fma_f32 v54, v50, v218, v52
	v_pk_fma_f32 v[122:123], v[50:51], v[196:197], v[122:123] op_sel_hi:[0,1,1]
	v_pk_fma_f32 v[124:125], v[50:51], v[198:199], v[124:125] op_sel_hi:[0,1,1]
	v_pk_fma_f32 v[126:127], v[50:51], v[200:201], v[126:127] op_sel_hi:[0,1,1]
	v_fma_f32 v55, v220, v219, v54
	v_pk_fma_f32 v[120:121], v[220:221], v[202:203], v[120:121] op_sel_hi:[0,1,1]
	v_pk_fma_f32 v[122:123], v[220:221], v[204:205], v[122:123] op_sel_hi:[0,1,1]
	v_cndmask_b32_e32 v48, v48, v55, vcc
	v_pk_fma_f32 v[124:125], v[220:221], v[206:207], v[124:125] op_sel_hi:[0,1,1]
	v_pk_fma_f32 v[126:127], v[220:221], v[208:209], v[126:127] op_sel_hi:[0,1,1]
	ds_read_b128 v[186:189], v145 offset:16896
	ds_read_b128 v[190:193], v145 offset:16912
	ds_read_b128 v[210:213], v145 offset:17664
	ds_read_b128 v[214:217], v145 offset:17680
	ds_read_b64 v[218:219], v56 offset:104
	ds_read_b32 v220, v146 offset:21312
	ds_read_b128 v[178:181], v145 offset:16640
	ds_read_b128 v[182:185], v145 offset:16656
	ds_read_b128 v[194:197], v145 offset:17152
	s_waitcnt lgkmcnt(9)
; #define LAS __attribute__((address_space(3)))
; __device__ __forceinline__ f32x2 fma2(f32x2 a, f32x2 b, f32x2 c) { return __builtin_elementwise_fma(a, b, c); }
; __device__ __forceinline__ float sum8(float x) { x += dppf<0x141>(x); x += dppf<0x4E>(x); x += dppf<0xB1>(x); return x; }
; __device__ __forceinline__ ROps8 r_ld8(const LAS float* B, int t, int kq, int vidx) {
;     ROps8 o; const LAS float* V = B + t * 320 + kq * 8;
; #pragma unroll
;     for (int h = 0; h < 2; ++h) { o.u[h] = *(const LAS f32x4*)(V + 4 * h); o.a[h] = *(const LAS f32x4*)(V + 64 + 4 * h); o.b[h] = *(const LAS f32x4*)(V + 128 + 4 * h); o.k[h] = *(const LAS f32x4*)(V + 192 + 4 * h); o.w[h] = *(const LAS f32x4*)(V + 256 + 4 * h); }
;     o.v = B[5120 + t * 16 + vidx]; o.sc = *(const LAS f32x2*)(B + 5376 + t * 2); return o;
; template <int TB> __device__ __forceinline__ void rwkv_block8(f32x2 (&S)[4], const LAS float* B, int kq, int vidx, float* yo) {
;     ...
;     for (int tt = 0; tt < SCAN_UNR; ++tt) {
;         const int t = t0 + tt;
;         const ROps8 n = r_ld8(B, (t + 1) & 15, kq, vidx);
;         const f32x2 a[4] = PAIRS(c.a), w[4] = PAIRS(c.w), u[4] = PAIRS(c.u), b[4] = PAIRS(c.b), k[4] = PAIRS(c.k);
;         const f32x2 ps = fma2(S[3], a[3], fma2(S[2], a[2], fma2(S[1], a[1], S[0] * a[0]))), py = fma2(S[3], w[3], fma2(S[2], w[2], fma2(S[1], w[1], S[0] * w[0])));
;         const float sa = sum8(ps.x + ps.y), yp = sum8(py.x + py.y);
;         const f32x2 sa2 = {sa, sa}, v2 = {c.v, c.v};
; #pragma unroll
;         for (int e = 0; e < 4; ++e) { S[e] = fma2(-u[e], S[e], S[e]); S[e] = fma2(sa2, b[e], S[e]); S[e] = fma2(v2, k[e], S[e]); }
;         const float y = yp + sa * c.sc.x + c.v * c.sc.y;
;         ykA = (kq == t) ? y : ykA; ykB = (kq + 8 == t) ? y : ykB;
;         c = n;
	v_pk_mul_f32 v[50:51], v[120:121], v[82:83]
	v_pk_mul_f32 v[52:53], v[120:121], v[106:107]
	v_pk_fma_f32 v[50:51], v[122:123], v[84:85], v[50:51]
	v_pk_fma_f32 v[52:53], v[122:123], v[108:109], v[52:53]
	v_pk_fma_f32 v[50:51], v[124:125], v[86:87], v[50:51]
	v_pk_fma_f32 v[52:53], v[124:125], v[110:111], v[52:53]
	v_pk_fma_f32 v[50:51], v[126:127], v[88:89], v[50:51]
	v_pk_fma_f32 v[52:53], v[126:127], v[112:113], v[52:53]
	v_add_f32_e32 v50, v50, v51
	v_add_f32_e32 v52, v52, v53
	ds_read_b128 v[198:201], v145 offset:17168
	v_add_f32_dpp v50, v50, v50 row_half_mirror row_mask:0xf bank_mask:0xf bound_ctrl:1
	v_add_f32_dpp v52, v52, v52 row_half_mirror row_mask:0xf bank_mask:0xf bound_ctrl:1
	ds_read_b128 v[202:205], v145 offset:17408
	v_add_f32_dpp v50, v50, v50 quad_perm:[2,3,0,1] row_mask:0xf bank_mask:0xf bound_ctrl:1
	v_add_f32_dpp v52, v52, v52 quad_perm:[2,3,0,1] row_mask:0xf bank_mask:0xf bound_ctrl:1
	ds_read_b128 v[206:209], v145 offset:17424
	v_add_f32_dpp v50, v50, v50 quad_perm:[1,0,3,2] row_mask:0xf bank_mask:0xf bound_ctrl:1
	v_add_f32_dpp v52, v52, v52 quad_perm:[1,0,3,2] row_mask:0xf bank_mask:0xf bound_ctrl:1
	v_pk_fma_f32 v[120:121], v[74:75], v[120:121], v[120:121] neg_lo:[1,0,0] neg_hi:[1,0,0]
	v_pk_fma_f32 v[122:123], v[76:77], v[122:123], v[122:123] neg_lo:[1,0,0] neg_hi:[1,0,0]
	v_pk_fma_f32 v[124:125], v[78:79], v[124:125], v[124:125] neg_lo:[1,0,0] neg_hi:[1,0,0]
	v_pk_fma_f32 v[126:127], v[80:81], v[126:127], v[126:127] neg_lo:[1,0,0] neg_hi:[1,0,0]
	v_cmp_eq_u32_e32 vcc, 4, v129
	v_pk_fma_f32 v[120:121], v[50:51], v[90:91], v[120:121] op_sel_hi:[0,1,1]
	v_fma_f32 v54, v50, v114, v52
	v_pk_fma_f32 v[122:123], v[50:51], v[92:93], v[122:123] op_sel_hi:[0,1,1]
	v_pk_fma_f32 v[124:125], v[50:51], v[94:95], v[124:125] op_sel_hi:[0,1,1]
	v_pk_fma_f32 v[126:127], v[50:51], v[96:97], v[126:127] op_sel_hi:[0,1,1]
	v_fma_f32 v55, v116, v115, v54
	v_pk_fma_f32 v[120:121], v[116:117], v[98:99], v[120:121] op_sel_hi:[0,1,1]
	v_pk_fma_f32 v[122:123], v[116:117], v[100:101], v[122:123] op_sel_hi:[0,1,1]
	v_cndmask_b32_e32 v48, v48, v55, vcc
	v_pk_fma_f32 v[124:125], v[116:117], v[102:103], v[124:125] op_sel_hi:[0,1,1]
	v_pk_fma_f32 v[126:127], v[116:117], v[104:105], v[126:127] op_sel_hi:[0,1,1]
	ds_read_b128 v[82:85], v145 offset:18176
	ds_read_b128 v[86:89], v145 offset:18192
	ds_read_b128 v[106:109], v145 offset:18944
	ds_read_b128 v[110:113], v145 offset:18960
	ds_read_b64 v[114:115], v56 offset:112
	ds_read_b32 v116, v146 offset:21376
	ds_read_b128 v[74:77], v145 offset:17920
	ds_read_b128 v[78:81], v145 offset:17936
	ds_read_b128 v[90:93], v145 offset:18432
	s_waitcnt lgkmcnt(9)
	v_pk_mul_f32 v[50:51], v[120:121], v[186:187]
	v_pk_mul_f32 v[52:53], v[120:121], v[210:211]
	v_pk_fma_f32 v[50:51], v[122:123], v[188:189], v[50:51]
	v_pk_fma_f32 v[52:53], v[122:123], v[212:213], v[52:53]
	v_pk_fma_f32 v[50:51], v[124:125], v[190:191], v[50:51]
	v_pk_fma_f32 v[52:53], v[124:125], v[214:215], v[52:53]
	v_pk_fma_f32 v[50:51], v[126:127], v[192:193], v[50:51]
	v_pk_fma_f32 v[52:53], v[126:127], v[216:217], v[52:53]
	v_add_f32_e32 v50, v50, v51
	v_add_f32_e32 v52, v52, v53
	ds_read_b128 v[94:97], v145 offset:18448
	v_add_f32_dpp v50, v50, v50 row_half_mirror row_mask:0xf bank_mask:0xf bound_ctrl:1
	v_add_f32_dpp v52, v52, v52 row_half_mirror row_mask:0xf bank_mask:0xf bound_ctrl:1
	ds_read_b128 v[98:101], v145 offset:18688
	v_add_f32_dpp v50, v50, v50 quad_perm:[2,3,0,1] row_mask:0xf bank_mask:0xf bound_ctrl:1
	v_add_f32_dpp v52, v52, v52 quad_perm:[2,3,0,1] row_mask:0xf bank_mask:0xf bound_ctrl:1
	ds_read_b128 v[102:105], v145 offset:18704
	v_add_f32_dpp v50, v50, v50 quad_perm:[1,0,3,2] row_mask:0xf bank_mask:0xf bound_ctrl:1
	v_add_f32_dpp v52, v52, v52 quad_perm:[1,0,3,2] row_mask:0xf bank_mask:0xf bound_ctrl:1
	v_pk_fma_f32 v[120:121], v[178:179], v[120:121], v[120:121] neg_lo:[1,0,0] neg_hi:[1,0,0]
	v_pk_fma_f32 v[122:123], v[180:181], v[122:123], v[122:123] neg_lo:[1,0,0] neg_hi:[1,0,0]
	v_pk_fma_f32 v[124:125], v[182:183], v[124:125], v[124:125] neg_lo:[1,0,0] neg_hi:[1,0,0]
	v_pk_fma_f32 v[126:127], v[184:185], v[126:127], v[126:127] neg_lo:[1,0,0] neg_hi:[1,0,0]
	v_cmp_eq_u32_e32 vcc, 5, v129
	v_pk_fma_f32 v[120:121], v[50:51], v[194:195], v[120:121] op_sel_hi:[0,1,1]
	v_fma_f32 v54, v50, v218, v52
	v_pk_fma_f32 v[122:123], v[50:51], v[196:197], v[122:123] op_sel_hi:[0,1,1]
	v_pk_fma_f32 v[124:125], v[50:51], v[198:199], v[124:125] op_sel_hi:[0,1,1]
	v_pk_fma_f32 v[126:127], v[50:51], v[200:201], v[126:127] op_sel_hi:[0,1,1]
	v_fma_f32 v55, v220, v219, v54
	v_pk_fma_f32 v[120:121], v[220:221], v[202:203], v[120:121] op_sel_hi:[0,1,1]
	v_pk_fma_f32 v[122:123], v[220:221], v[204:205], v[122:123] op_sel_hi:[0,1,1]
	v_cndmask_b32_e32 v48, v48, v55, vcc
	v_pk_fma_f32 v[124:125], v[220:221], v[206:207], v[124:125] op_sel_hi:[0,1,1]
	v_pk_fma_f32 v[126:127], v[220:221], v[208:209], v[126:127] op_sel_hi:[0,1,1]
	ds_read_b128 v[186:189], v145 offset:19456
	ds_read_b128 v[190:193], v145 offset:19472
	ds_read_b128 v[210:213], v145 offset:20224
	ds_read_b128 v[214:217], v145 offset:20240
	ds_read_b64 v[218:219], v56 offset:120
	ds_read_b32 v220, v146 offset:21440
	ds_read_b128 v[178:181], v145 offset:19200
	ds_read_b128 v[182:185], v145 offset:19216
	ds_read_b128 v[194:197], v145 offset:19712
	s_waitcnt lgkmcnt(9)
; template <int TB> __device__ __forceinline__ void rwkv_block8(f32x2 (&S)[4], const LAS float* B, int kq, int vidx, float* yo) {
;     ...
;     for (int tt = 0; tt < SCAN_UNR; ++tt) {
;         const int t = t0 + tt;
;         const ROps8 n = r_ld8(B, (t + 1) & 15, kq, vidx);
;         const f32x2 a[4] = PAIRS(c.a), w[4] = PAIRS(c.w), u[4] = PAIRS(c.u), b[4] = PAIRS(c.b), k[4] = PAIRS(c.k);
;         const f32x2 ps = fma2(S[3], a[3], fma2(S[2], a[2], fma2(S[1], a[1], S[0] * a[0]))), py = fma2(S[3], w[3], fma2(S[2], w[2], fma2(S[1], w[1], S[0] * w[0])));
;         const float sa = sum8(ps.x + ps.y), yp = sum8(py.x + py.y);
;         const f32x2 sa2 = {sa, sa}, v2 = {c.v, c.v};
; #pragma unroll
;         for (int e = 0; e < 4; ++e) { S[e] = fma2(-u[e], S[e], S[e]); S[e] = fma2(sa2, b[e], S[e]); S[e] = fma2(v2, k[e], S[e]); }
;         const float y = yp + sa * c.sc.x + c.v * c.sc.y;
;         ykA = (kq == t) ? y : ykA; ykB = (kq + 8 == t) ? y : ykB;
;         c = n;
;     }
;     yo[(size_t)kq * RW] = ykA;
;     if (TB == 16) yo[(size_t)(kq + 8) * RW] = ykB;
; __device__ __forceinline__ void phase_scan(Ctx& C, int i) {
;     ...
;         for (int blk = 0; blk < SC_NBLK; ++blk) {
;             RELAUNDER;
;             R_DESC(blk, m0, tb, head, quarter, b, isprompt)
;             const bool last = isprompt ? (blk == 127) : true;
;             if (blk + 1 < SC_NBLK) R_STAGE_LOAD(blk + 1);
;             const LAS float* B = buf0 + (blk & 1) * RBUF;
;             const int row = quarter * 16 + w * 8 + sub;
;             float* yo = YRAW + m0 * RW + head * 64 + row;
;             if (cw) {
;             if (tb == 16) rwkv_block8<16>(S, B, kq, w * 8 + sub, yo); else rwkv_block8<8>(S, B, kq, w * 8 + sub, yo);
;             if (last) {
;                 float* So = (isprompt ? C.out + O_RWKV_P + ((size_t)(i * NB + b) * RH + head) * 4096 : C.out + O_RWKV_S + ((size_t)(i * SB + b) * RH + head) * 4096);
;                 *(f32x4*)(So + row * 64 + kq * 8) = (f32x4){S[0].x, S[0].y, S[1].x, S[1].y}; *(f32x4*)(So + row * 64 + kq * 8 + 4) = (f32x4){S[2].x, S[2].y, S[3].x, S[3].y};
;                 S[0] = (f32x2){Snext.x, Snext.y}; S[1] = (f32x2){Snext.z, Snext.w}; S[2] = (f32x2){Snext1.x, Snext1.y}; S[3] = (f32x2){Snext1.z, Snext1.w};
;             }
;             }
;             if (blk + 1 < SC_NBLK) R_STAGE_WRITE(blk + 1);
;             __syncthreads();
;         }
	v_pk_mul_f32 v[50:51], v[120:121], v[82:83]
	v_pk_mul_f32 v[52:53], v[120:121], v[106:107]
	v_pk_fma_f32 v[50:51], v[122:123], v[84:85], v[50:51]
	v_pk_fma_f32 v[52:53], v[122:123], v[108:109], v[52:53]
	v_pk_fma_f32 v[50:51], v[124:125], v[86:87], v[50:51]
	v_pk_fma_f32 v[52:53], v[124:125], v[110:111], v[52:53]
	v_pk_fma_f32 v[50:51], v[126:127], v[88:89], v[50:51]
	v_pk_fma_f32 v[52:53], v[126:127], v[112:113], v[52:53]
	v_add_f32_e32 v50, v50, v51
	v_add_f32_e32 v52, v52, v53
	ds_read_b128 v[198:201], v145 offset:19728
	v_add_f32_dpp v50, v50, v50 row_half_mirror row_mask:0xf bank_mask:0xf bound_ctrl:1
	v_add_f32_dpp v52, v52, v52 row_half_mirror row_mask:0xf bank_mask:0xf bound_ctrl:1
	ds_read_b128 v[202:205], v145 offset:19968
	v_add_f32_dpp v50, v50, v50 quad_perm:[2,3,0,1] row_mask:0xf bank_mask:0xf bound_ctrl:1
	v_add_f32_dpp v52, v52, v52 quad_perm:[2,3,0,1] row_mask:0xf bank_mask:0xf bound_ctrl:1
	ds_read_b128 v[206:209], v145 offset:19984
	v_add_f32_dpp v50, v50, v50 quad_perm:[1,0,3,2] row_mask:0xf bank_mask:0xf bound_ctrl:1
	v_add_f32_dpp v52, v52, v52 quad_perm:[1,0,3,2] row_mask:0xf bank_mask:0xf bound_ctrl:1
	v_pk_fma_f32 v[120:121], v[74:75], v[120:121], v[120:121] neg_lo:[1,0,0] neg_hi:[1,0,0]
	v_pk_fma_f32 v[122:123], v[76:77], v[122:123], v[122:123] neg_lo:[1,0,0] neg_hi:[1,0,0]
	v_pk_fma_f32 v[124:125], v[78:79], v[124:125], v[124:125] neg_lo:[1,0,0] neg_hi:[1,0,0]
	v_pk_fma_f32 v[126:127], v[80:81], v[126:127], v[126:127] neg_lo:[1,0,0] neg_hi:[1,0,0]
	v_cmp_eq_u32_e32 vcc, 6, v129
	v_pk_fma_f32 v[120:121], v[50:51], v[90:91], v[120:121] op_sel_hi:[0,1,1]
	v_fma_f32 v54, v50, v114, v52
	v_pk_fma_f32 v[122:123], v[50:51], v[92:93], v[122:123] op_sel_hi:[0,1,1]
	v_pk_fma_f32 v[124:125], v[50:51], v[94:95], v[124:125] op_sel_hi:[0,1,1]
	v_pk_fma_f32 v[126:127], v[50:51], v[96:97], v[126:127] op_sel_hi:[0,1,1]
	v_fma_f32 v55, v116, v115, v54
	v_pk_fma_f32 v[120:121], v[116:117], v[98:99], v[120:121] op_sel_hi:[0,1,1]
	v_pk_fma_f32 v[122:123], v[116:117], v[100:101], v[122:123] op_sel_hi:[0,1,1]
	v_cndmask_b32_e32 v48, v48, v55, vcc
	v_pk_fma_f32 v[124:125], v[116:117], v[102:103], v[124:125] op_sel_hi:[0,1,1]
	v_pk_fma_f32 v[126:127], v[116:117], v[104:105], v[126:127] op_sel_hi:[0,1,1]
	s_waitcnt lgkmcnt(0)
	v_pk_mul_f32 v[50:51], v[120:121], v[186:187]
	v_pk_mul_f32 v[52:53], v[120:121], v[210:211]
	v_pk_fma_f32 v[50:51], v[122:123], v[188:189], v[50:51]
	v_pk_fma_f32 v[52:53], v[122:123], v[212:213], v[52:53]
	v_pk_fma_f32 v[50:51], v[124:125], v[190:191], v[50:51]
	v_pk_fma_f32 v[52:53], v[124:125], v[214:215], v[52:53]
	v_pk_fma_f32 v[50:51], v[126:127], v[192:193], v[50:51]
	v_pk_fma_f32 v[52:53], v[126:127], v[216:217], v[52:53]
	v_add_f32_e32 v50, v50, v51
	v_add_f32_e32 v52, v52, v53
	v_pk_fma_f32 v[120:121], v[178:179], v[120:121], v[120:121] neg_lo:[1,0,0] neg_hi:[1,0,0]
	v_add_f32_dpp v50, v50, v50 row_half_mirror row_mask:0xf bank_mask:0xf bound_ctrl:1
	v_add_f32_dpp v52, v52, v52 row_half_mirror row_mask:0xf bank_mask:0xf bound_ctrl:1
	v_pk_fma_f32 v[122:123], v[180:181], v[122:123], v[122:123] neg_lo:[1,0,0] neg_hi:[1,0,0]
	v_add_f32_dpp v50, v50, v50 quad_perm:[2,3,0,1] row_mask:0xf bank_mask:0xf bound_ctrl:1
	v_add_f32_dpp v52, v52, v52 quad_perm:[2,3,0,1] row_mask:0xf bank_mask:0xf bound_ctrl:1
	v_pk_fma_f32 v[124:125], v[182:183], v[124:125], v[124:125] neg_lo:[1,0,0] neg_hi:[1,0,0]
	v_add_f32_dpp v50, v50, v50 quad_perm:[1,0,3,2] row_mask:0xf bank_mask:0xf bound_ctrl:1
	v_add_f32_dpp v52, v52, v52 quad_perm:[1,0,3,2] row_mask:0xf bank_mask:0xf bound_ctrl:1
	v_pk_fma_f32 v[126:127], v[184:185], v[126:127], v[126:127] neg_lo:[1,0,0] neg_hi:[1,0,0]
	v_cmp_eq_u32_e32 vcc, 7, v129
	v_pk_fma_f32 v[120:121], v[50:51], v[194:195], v[120:121] op_sel_hi:[0,1,1]
	v_fma_f32 v54, v50, v218, v52
	v_pk_fma_f32 v[122:123], v[50:51], v[196:197], v[122:123] op_sel_hi:[0,1,1]
	v_pk_fma_f32 v[124:125], v[50:51], v[198:199], v[124:125] op_sel_hi:[0,1,1]
	v_pk_fma_f32 v[126:127], v[50:51], v[200:201], v[126:127] op_sel_hi:[0,1,1]
	v_fma_f32 v55, v220, v219, v54
	v_pk_fma_f32 v[120:121], v[220:221], v[202:203], v[120:121] op_sel_hi:[0,1,1]
	v_pk_fma_f32 v[122:123], v[220:221], v[204:205], v[122:123] op_sel_hi:[0,1,1]
	v_cndmask_b32_e32 v48, v48, v55, vcc
	v_pk_fma_f32 v[124:125], v[220:221], v[206:207], v[124:125] op_sel_hi:[0,1,1]
	v_pk_fma_f32 v[126:127], v[220:221], v[208:209], v[126:127] op_sel_hi:[0,1,1]
	s_cmpk_gt_u32 s41, 0x7e
	s_cbranch_scc1 .Lrwkv16_exit
	v_lshlrev_b32_e32 v2, 11, v129
	v_lshl_add_u64 v[36:37], v[130:131], 0, v[2:3]
	global_store_dword v[36:37], v49, off
	s_mov_b32 s4, 0x4000
	s_mov_b32 s5, 0
	v_lshl_add_u64 v[36:37], v[36:37], 0, s[4:5]
	global_store_dword v[36:37], v48, off
	s_mov_b32 s4, 0x8000
	v_lshl_add_u64 v[130:131], v[130:131], 0, s[4:5]
	s_add_i32 s41, s41, 1
	s_xor_b32 s48, s48, 0x5480
	s_lshl_b32 s4, s59, 2
	s_add_i32 s4, s48, s4
	v_add_u32_e32 v145, s48, v128
	v_lshl_add_u32 v146, v133, 2, s4
	s_add_i32 s49, s48, 0x5400
	v_mov_b32_e32 v49, 0
	v_mov_b32_e32 v48, 0
	s_waitcnt lgkmcnt(0)
	s_barrier
	s_branch .Lrwkv16_top
.Lrwkv16_exit:
	v_lshlrev_b32_e32 v2, 11, v129
	v_lshl_add_u64 v[36:37], v[130:131], 0, v[2:3]
	global_store_dword v[36:37], v49, off
	v_add_co_u32_e32 v36, vcc, 0x4000, v36
	v_mov_b32_e32 v39, v127
	s_nop 0
	v_addc_co_u32_e32 v37, vcc, 0, v37, vcc
	global_store_dword v[36:37], v48, off
	v_mov_b32_e32 v38, v126
	v_mov_b32_e32 v37, v125
	v_mov_b32_e32 v36, v124
	v_mov_b32_e32 v43, v123
	v_mov_b32_e32 v42, v122
	v_mov_b32_e32 v41, v121
	v_mov_b32_e32 v40, v120
	s_andn2_b64 vcc, exec, s[44:45]
	s_cbranch_vccz .LBB0_1040
	s_branch .LBB0_1041
